# baseline (speedup 1.0000x reference)
; DI int my_block() { int b = blockIdx.x; asm volatile("" : "+s"(b)); return b; }
; #define G_STAGE(bufoff, gbase, voff) do { _Pragma("unroll") for (int _i = 0; _i < 2; ++_i) \
;         __builtin_amdgcn_global_load_lds((const unsigned*)((const char*)(gbase) + (voff)[_i]), (LAS unsigned*)(lds + (bufoff) + ldsw + _i * 8192), 16, 0, 0); } while (0)
; #define G_WAIT_V(n) asm volatile("s_waitcnt vmcnt(" #n ")" ::: "memory")
; #define G_BAR __builtin_amdgcn_s_barrier()
;   DI const char* aptr(const Unit& u) const { return (const char*)(h + (size_t)u.pm * 256 * DM); }
;   DI const char* bptr(const Unit& u) const { return (const char*)(winT + (size_t)u.pn * 256 * DM); }
;   DI bool next(int i, Unit& u) const { const int L = i * G + c; if (L >= nunits) return false; u.kind = 0; decode_unit(L, 65, 32, u.pm, u.pn); return true; }
;   DI const char* aptr(const Unit& u) const { return (const char*)(y + (size_t)u.pm * 256 * DM + (u.pn >> 3) * 512); }
;   DI const char* bptr(const Unit& u) const { return (const char*)(wbT + (size_t)u.pn * 256 * 512); }
;   DI const char* aptr(const Unit& u) const { return (const char*)(h + (size_t)u.pm * 256 * DM); }
;   DI const char* bptr(const Unit& u) const { return (const char*)(wgT + (size_t)u.pn * 64 * DM); }
; template <class J>
; DI void gemm_phase(LAS unsigned char* lds, const J& job) {
;     ...
;   const int aoff = lds_byte(wr * 64 + fr, fq * 8), boff = lds_byte(wc * 32 + fr, fq * 8);
;     ...
;   Unit cur, nxt; int ui = 0;
;   if (!job.next(0, cur)) return;
;   f32x4 acc[2][2][4][2];
; #pragma unroll
;   for (int a = 0; a < 2; ++a)
; #pragma unroll
;     for (int b = 0; b < 2; ++b)
; #pragma unroll
;       for (int m = 0; m < 4; ++m)
; #pragma unroll
;         for (int n = 0; n < 2; ++n) acc[a][b][m][n] = (f32x4){0.f, 0.f, 0.f, 0.f};
;   bf16x8 At[4][2], B0[2][2], B1[2][2];
;   const char* cA = job.aptr(cur); const char* cB = job.bptr(cur);
;   const int koff = (my_block() & 7) * (nt >> 3), kmask = nt - 1;
;     ...
;   G_STAGE(G_SB(0, 0), cB + G_KT(0), voffB); G_STAGE(G_SA(0, 0), cA + G_KT(0), voffA); G_STAGE(G_SB(0, 1), cB + hstepB + G_KT(0), voffB); G_STAGE(G_SA(0, 1), cA + hstepA + G_KT(0), voffA);
;   if (wr == 1) G_BAR;
;   G_WAIT_V(4); G_BAR;
;   G_STAGE(G_SB(1, 0), cB + G_KT(1), voffB); G_STAGE(G_SA(1, 0), cA + G_KT(1), voffA); G_STAGE(G_SB(1, 1), cB + hstepB + G_KT(1), voffB);
;   G_WAIT_V(6); G_BAR;
.LBB0_34:
	v_bfe_u32 v161, v0, 4, 2
	v_and_b32_e32 v160, 15, v0
	v_lshlrev_b32_e32 v1, 4, v161
	v_lshlrev_b32_e32 v0, 2, v0
	v_lshl_or_b32 v1, v160, 6, v1
	s_lshl_b32 s0, s5, 13
	v_and_b32_e32 v0, 32, v0
	v_bitop3_b32 v2, v1, s0, v0 bitop3:0xde
	s_lshl_b32 s0, s6, 5
	s_and_b32 s83, s0, 0x60
	s_lshl_b32 s67, s5, 6
	s_lshl_b32 s0, s83, 7
	s_or_b32 s86, s24, 0x80
	v_bitop3_b32 v162, v1, s0, v0 bitop3:0xde
	v_add_u32_e32 v221, 0x10100, v162
	s_add_u32 s0, s68, s86
	s_addc_u32 s1, s69, 0
	s_add_i32 m0, s25, 0x18000
	v_lshl_add_u64 v[0:1], s[0:1], 0, v[146:147]
	v_mov_b32_e32 v153, v147
	s_waitcnt vmcnt(4)
	s_barrier
	global_load_lds_dwordx4 v[0:1], off
	s_add_i32 m0, s25, 0x1a000
	v_lshl_add_u64 v[0:1], s[0:1], 0, v[152:153]
	s_add_u32 s0, s70, s86
	v_mov_b32_e32 v149, v147
	s_addc_u32 s1, s71, 0
	s_add_i32 s87, s25, 0x8000
	v_mov_b32_e32 v151, v147
	global_load_lds_dwordx4 v[0:1], off
	v_lshl_add_u64 v[0:1], s[0:1], 0, v[148:149]
	s_mov_b32 m0, s87
	s_add_i32 s94, s25, 0xa000
	global_load_lds_dwordx4 v[0:1], off
	v_lshl_add_u64 v[0:1], s[0:1], 0, v[150:151]
	s_add_u32 s0, s7, s86
	s_mov_b32 m0, s94
	s_addc_u32 s1, s18, 0
	global_load_lds_dwordx4 v[0:1], off
	s_add_i32 m0, s25, 0x1c000
	v_lshl_add_u64 v[0:1], s[0:1], 0, v[146:147]
	global_load_lds_dwordx4 v[0:1], off
	v_lshl_add_u64 v[0:1], s[0:1], 0, v[152:153]
	s_add_i32 m0, s25, 0x1e000
	v_readlane_b32 s0, v255, 14
	global_load_lds_dwordx4 v[0:1], off
	v_readlane_b32 s1, v255, 15
	s_and_b64 s[0:1], s[0:1], exec
	s_waitcnt lgkmcnt(0)
	s_cselect_b32 s9, s17, s9
	s_cselect_b32 s8, s16, s8
	s_lshl_b32 s0, s4, 9
	s_waitcnt vmcnt(6)
	s_or_b32 s96, s0, 0x180
	s_and_b32 s0, s4, 7
	s_lshl_b32 s56, s0, 9
	s_bitset1_b32 s56, 7
	s_mov_b32 s45, 0
	v_add_u32_e32 v163, 0x100, v2
	s_barrier

; #define G_STAGE(bufoff, gbase, voff) do { _Pragma("unroll") for (int _i = 0; _i < 2; ++_i) \
;         __builtin_amdgcn_global_load_lds((const unsigned*)((const char*)(gbase) + (voff)[_i]), (LAS unsigned*)(lds + (bufoff) + ldsw + _i * 8192), 16, 0, 0); } while (0)
; #define G_LDA(dst, b, h) do { _Pragma("unroll") for (int m = 0; m < 4; ++m) _Pragma("unroll") for (int k = 0; k < 2; ++k) dst[m][k] = *(const LAS bf16x8*)(lds + G_SA(b, h) + aoff + m * 2048 + k * 1024); } while (0)
; #define G_LDB(dst, b, h) do { _Pragma("unroll") for (int n = 0; n < 2; ++n) _Pragma("unroll") for (int k = 0; k < 2; ++k) dst[n][k] = *(const LAS bf16x8*)(lds + G_SB(b, h) + boff + n * 2048 + k * 1024); } while (0)
; #define G_MMA(ai, bj, At, Bt) do { __builtin_amdgcn_s_setprio(1); _Pragma("unroll") for (int m = 0; m < 4; ++m) _Pragma("unroll") for (int n = 0; n < 2; ++n) _Pragma("unroll") for (int k = 0; k < 2; ++k) \
;         acc[ai][bj][m][n] = __builtin_amdgcn_mfma_f32_16x16x32_bf16(Bt[n][k], At[m][k], acc[ai][bj][m][n], 0, 0, 0); __builtin_amdgcn_s_setprio(0); } while (0)
; #define G_WAIT_L(n) asm volatile("s_waitcnt lgkmcnt(" #n ")" ::: "memory")
; #define G_BAR __builtin_amdgcn_s_barrier()
; #define G_SCHED __builtin_amdgcn_sched_barrier(0)
; template <class J>
; DI void gemm_phase(LAS unsigned char* lds, const J& job) {
;     ...
;       const bool last = (t == nt - 2);
;       const char* a1 = cA + G_KT(t + 1);
;       const char* a2 = last ? nA + G_KT(0) : cA + G_KT(t + 2); const char* b2 = last ? nB + G_KT(0) : cB + G_KT(t + 2);
;       const char* a3 = last ? nA + G_KT(1) : cA + G_KT(t + 3); const char* b3 = last ? nB + G_KT(1) : cB + G_KT(t + 3);
;       G_LDB(B0, 0, 0); G_SCHED; G_LDA(At, 0, 0); G_STAGE(G_SA(1, 1), a1 + hstepA, voffA);
;       G_WAIT_L(8); G_BAR; G_WAIT_L(0); G_MMA(0, 0, At, B0); G_BAR; G_SCHED;
;       G_LDB(B1, 0, 1); G_STAGE(G_SB(0, 0), b2, voffB);
;       G_BAR; G_WAIT_L(0); G_MMA(0, 1, At, B1); G_BAR;
;       G_LDA(At, 0, 1); G_STAGE(G_SA(0, 0), a2, voffA);
;       G_BAR; G_WAIT_L(0); G_MMA(1, 0, At, B0); G_BAR; G_SCHED;
.LBB0_42:
	s_add_i32 s1, s57, 0xffffff80
	s_and_b32 s0, s44, 0xf80
	s_and_b32 s1, s1, 0xf00
	s_add_u32 s2, s70, s1
	s_addc_u32 s72, s71, 0
	s_add_u32 s1, s68, s1
	s_addc_u32 s73, s69, 0
	s_and_b32 s74, s57, 0xf80
	s_add_u32 s80, s70, s74
	s_addc_u32 s75, s71, 0
	s_add_u32 s54, s68, s74
	s_addc_u32 s55, s69, 0
	s_cmp_eq_u32 s7, 28
	s_cselect_b32 s77, vcc_lo, s72
	s_cselect_b32 s76, s47, s2
	s_cselect_b32 s79, s33, s73
	s_cselect_b32 s78, vcc_hi, s1
	s_cselect_b32 s75, s4, s75
	s_cselect_b32 s74, s97, s80
	s_cselect_b32 s73, s6, s55
	s_cselect_b32 s72, s5, s54
	s_add_i32 s2, s84, 0x100
	ds_read_b128 v[128:131], v221
	ds_read_b128 v[132:135], v221 offset:1024
	ds_read_b128 v[136:139], v221 offset:2048
	ds_read_b128 v[140:143], v221 offset:3072
	s_add_u32 s0, s21, s0
	s_addc_u32 s1, s23, 0
	s_add_i32 m0, s25, 0xc000
	ds_read_b128 v[154:157], v163
	ds_read_b128 v[164:167], v163 offset:1024
	ds_read_b128 v[168:171], v163 offset:2048
	ds_read_b128 v[172:175], v163 offset:3072
	ds_read_b128 v[176:179], v163 offset:4096
	ds_read_b128 v[180:183], v163 offset:5120
	ds_read_b128 v[184:187], v163 offset:6144
	ds_read_b128 v[188:191], v163 offset:7168
	global_load_lds_dwordx4 v148, s[0:1]
	s_add_i32 m0, s25, 0xe000
	s_nop 0
	global_load_lds_dwordx4 v150, s[0:1]
	s_waitcnt lgkmcnt(8)
	s_barrier
	s_waitcnt lgkmcnt(0)
	v_mfma_f32_16x16x32_bf16 v[124:127], v[128:131], v[154:157], v[124:127]
	v_mfma_f32_16x16x32_bf16 v[120:123], v[136:139], v[154:157], v[120:123]
	v_mfma_f32_16x16x32_bf16 v[108:111], v[128:131], v[168:171], v[108:111]
	v_mfma_f32_16x16x32_bf16 v[104:107], v[136:139], v[168:171], v[104:107]
	v_mfma_f32_16x16x32_bf16 v[92:95], v[128:131], v[176:179], v[92:95]
	v_mfma_f32_16x16x32_bf16 v[88:91], v[136:139], v[176:179], v[88:91]
	v_mfma_f32_16x16x32_bf16 v[76:79], v[128:131], v[184:187], v[76:79]
	v_mfma_f32_16x16x32_bf16 v[72:75], v[136:139], v[184:187], v[72:75]
	v_mfma_f32_16x16x32_bf16 v[124:127], v[132:135], v[164:167], v[124:127]
	v_mfma_f32_16x16x32_bf16 v[120:123], v[140:143], v[164:167], v[120:123]
	v_mfma_f32_16x16x32_bf16 v[108:111], v[132:135], v[172:175], v[108:111]
	v_mfma_f32_16x16x32_bf16 v[104:107], v[140:143], v[172:175], v[104:107]
	v_mfma_f32_16x16x32_bf16 v[92:95], v[132:135], v[180:183], v[92:95]
	v_mfma_f32_16x16x32_bf16 v[88:91], v[140:143], v[180:183], v[88:91]
	v_mfma_f32_16x16x32_bf16 v[76:79], v[132:135], v[188:191], v[76:79]
	v_mfma_f32_16x16x32_bf16 v[72:75], v[140:143], v[188:191], v[72:75]
	s_barrier
	s_add_i32 s54, s85, 0x100
	s_add_i32 s0, s2, s14
	ds_read_b128 v[192:195], v221 offset:16384
	ds_read_b128 v[196:199], v221 offset:17408
	ds_read_b128 v[200:203], v221 offset:18432
	ds_read_b128 v[204:207], v221 offset:19456
	s_mov_b32 m0, s0
	s_nop 0
	global_load_lds_dwordx4 v146, s[78:79]
	s_add_i32 m0, s0, 0x2000
	s_nop 0
	global_load_lds_dwordx4 v152, s[78:79]
	s_barrier
	s_waitcnt lgkmcnt(0)
	v_mfma_f32_16x16x32_bf16 v[116:119], v[192:195], v[154:157], v[116:119]
	v_mfma_f32_16x16x32_bf16 v[112:115], v[200:203], v[154:157], v[112:115]
	v_mfma_f32_16x16x32_bf16 v[100:103], v[192:195], v[168:171], v[100:103]
	v_mfma_f32_16x16x32_bf16 v[96:99], v[200:203], v[168:171], v[96:99]
	v_mfma_f32_16x16x32_bf16 v[84:87], v[192:195], v[176:179], v[84:87]
	v_mfma_f32_16x16x32_bf16 v[80:83], v[200:203], v[176:179], v[80:83]
	v_mfma_f32_16x16x32_bf16 v[68:71], v[192:195], v[184:187], v[68:71]
	v_mfma_f32_16x16x32_bf16 v[64:67], v[200:203], v[184:187], v[64:67]
	v_mfma_f32_16x16x32_bf16 v[116:119], v[196:199], v[164:167], v[116:119]
	v_mfma_f32_16x16x32_bf16 v[112:115], v[204:207], v[164:167], v[112:115]
	v_mfma_f32_16x16x32_bf16 v[100:103], v[196:199], v[172:175], v[100:103]
	v_mfma_f32_16x16x32_bf16 v[96:99], v[204:207], v[172:175], v[96:99]
	v_mfma_f32_16x16x32_bf16 v[84:87], v[196:199], v[180:183], v[84:87]
	v_mfma_f32_16x16x32_bf16 v[80:83], v[204:207], v[180:183], v[80:83]
	v_mfma_f32_16x16x32_bf16 v[68:71], v[196:199], v[188:191], v[68:71]
	v_mfma_f32_16x16x32_bf16 v[64:67], v[204:207], v[188:191], v[64:67]
	s_mov_b32 m0, s25
	s_barrier
	ds_read_b128 v[154:157], v163 offset:16384
	ds_read_b128 v[164:167], v163 offset:17408
	ds_read_b128 v[168:171], v163 offset:18432
	ds_read_b128 v[172:175], v163 offset:19456
	ds_read_b128 v[176:179], v163 offset:20480
	ds_read_b128 v[180:183], v163 offset:21504
	ds_read_b128 v[184:187], v163 offset:22528
	ds_read_b128 v[188:191], v163 offset:23552
	global_load_lds_dwordx4 v148, s[76:77]
	s_mov_b32 m0, s36
	s_nop 0
	global_load_lds_dwordx4 v150, s[76:77]
	s_barrier
	s_waitcnt lgkmcnt(0)
	v_mfma_f32_16x16x32_bf16 v[60:63], v[128:131], v[154:157], v[60:63]
	v_mfma_f32_16x16x32_bf16 v[56:59], v[136:139], v[154:157], v[56:59]
	v_mfma_f32_16x16x32_bf16 v[44:47], v[128:131], v[168:171], v[44:47]
	v_mfma_f32_16x16x32_bf16 v[40:43], v[136:139], v[168:171], v[40:43]
	v_mfma_f32_16x16x32_bf16 v[28:31], v[128:131], v[176:179], v[28:31]
	v_mfma_f32_16x16x32_bf16 v[24:27], v[136:139], v[176:179], v[24:27]
	v_mfma_f32_16x16x32_bf16 v[20:23], v[128:131], v[184:187], v[20:23]
	v_mfma_f32_16x16x32_bf16 v[12:15], v[136:139], v[184:187], v[12:15]
	v_mfma_f32_16x16x32_bf16 v[60:63], v[132:135], v[164:167], v[60:63]
	v_mfma_f32_16x16x32_bf16 v[56:59], v[140:143], v[164:167], v[56:59]
	v_mfma_f32_16x16x32_bf16 v[44:47], v[132:135], v[172:175], v[44:47]
	v_mfma_f32_16x16x32_bf16 v[40:43], v[140:143], v[172:175], v[40:43]
	v_mfma_f32_16x16x32_bf16 v[28:31], v[132:135], v[180:183], v[28:31]
	v_mfma_f32_16x16x32_bf16 v[24:27], v[140:143], v[180:183], v[24:27]
	v_mfma_f32_16x16x32_bf16 v[20:23], v[132:135], v[188:191], v[20:23]
	v_mfma_f32_16x16x32_bf16 v[12:15], v[140:143], v[188:191], v[12:15]
	s_barrier
; #define G_STAGE(bufoff, gbase, voff) do { _Pragma("unroll") for (int _i = 0; _i < 2; ++_i) \
;         __builtin_amdgcn_global_load_lds((const unsigned*)((const char*)(gbase) + (voff)[_i]), (LAS unsigned*)(lds + (bufoff) + ldsw + _i * 8192), 16, 0, 0); } while (0)
; #define G_LDA(dst, b, h) do { _Pragma("unroll") for (int m = 0; m < 4; ++m) _Pragma("unroll") for (int k = 0; k < 2; ++k) dst[m][k] = *(const LAS bf16x8*)(lds + G_SA(b, h) + aoff + m * 2048 + k * 1024); } while (0)
; #define G_LDB(dst, b, h) do { _Pragma("unroll") for (int n = 0; n < 2; ++n) _Pragma("unroll") for (int k = 0; k < 2; ++k) dst[n][k] = *(const LAS bf16x8*)(lds + G_SB(b, h) + boff + n * 2048 + k * 1024); } while (0)
; #define G_MMA(ai, bj, At, Bt) do { __builtin_amdgcn_s_setprio(1); _Pragma("unroll") for (int m = 0; m < 4; ++m) _Pragma("unroll") for (int n = 0; n < 2; ++n) _Pragma("unroll") for (int k = 0; k < 2; ++k) \
;         acc[ai][bj][m][n] = __builtin_amdgcn_mfma_f32_16x16x32_bf16(Bt[n][k], At[m][k], acc[ai][bj][m][n], 0, 0, 0); __builtin_amdgcn_s_setprio(0); } while (0)
; #define G_WAIT_V(n) asm volatile("s_waitcnt vmcnt(" #n ")" ::: "memory")
; #define G_WAIT_L(n) asm volatile("s_waitcnt lgkmcnt(" #n ")" ::: "memory")
; #define G_BAR __builtin_amdgcn_s_barrier()
; #define G_SCHED __builtin_amdgcn_sched_barrier(0)
; template <class J>
; DI void gemm_phase(LAS unsigned char* lds, const J& job) {
;     ...
;       G_STAGE(G_SB(0, 1), b2 + hstepB, voffB);
;       G_WAIT_V(6); G_BAR; G_MMA(1, 1, At, B1); G_BAR;
;       G_LDB(B0, 1, 0); G_SCHED; G_LDA(At, 1, 0); G_STAGE(G_SA(0, 1), a2 + hstepA, voffA);
;       G_WAIT_L(8); G_BAR; G_WAIT_L(0); G_MMA(0, 0, At, B0); G_BAR; G_SCHED;
;       G_LDB(B1, 1, 1); G_STAGE(G_SB(1, 0), b3, voffB);
;       G_BAR; G_WAIT_L(0); G_MMA(0, 1, At, B1); G_BAR;
;       G_LDA(At, 1, 1); G_STAGE(G_SA(1, 0), a3, voffA);
	s_add_u32 s0, s78, 0x80000
	s_addc_u32 s1, s79, 0
	s_add_i32 s2, s54, s14
	s_mov_b32 m0, s2
	s_nop 0
	global_load_lds_dwordx4 v146, s[0:1]
	s_add_i32 m0, s2, 0x2000
	s_nop 0
	global_load_lds_dwordx4 v152, s[0:1]
	s_waitcnt vmcnt(6)
	s_barrier
	v_mfma_f32_16x16x32_bf16 v[52:55], v[192:195], v[154:157], v[52:55]
	v_mfma_f32_16x16x32_bf16 v[48:51], v[200:203], v[154:157], v[48:51]
	v_mfma_f32_16x16x32_bf16 v[36:39], v[192:195], v[168:171], v[36:39]
	v_mfma_f32_16x16x32_bf16 v[32:35], v[200:203], v[168:171], v[32:35]
	v_mfma_f32_16x16x32_bf16 v[16:19], v[192:195], v[176:179], v[16:19]
	v_mfma_f32_16x16x32_bf16 v[8:11], v[200:203], v[176:179], v[8:11]
	v_mfma_f32_16x16x32_bf16 v[4:7], v[192:195], v[184:187], v[4:7]
	v_mfma_f32_16x16x32_bf16 v[0:3], v[200:203], v[184:187], v[0:3]
	v_mfma_f32_16x16x32_bf16 v[52:55], v[196:199], v[164:167], v[52:55]
	v_mfma_f32_16x16x32_bf16 v[48:51], v[204:207], v[164:167], v[48:51]
	v_mfma_f32_16x16x32_bf16 v[36:39], v[196:199], v[172:175], v[36:39]
	v_mfma_f32_16x16x32_bf16 v[32:35], v[204:207], v[172:175], v[32:35]
	v_mfma_f32_16x16x32_bf16 v[16:19], v[196:199], v[180:183], v[16:19]
	v_mfma_f32_16x16x32_bf16 v[8:11], v[204:207], v[180:183], v[8:11]
	v_mfma_f32_16x16x32_bf16 v[4:7], v[196:199], v[188:191], v[4:7]
	v_mfma_f32_16x16x32_bf16 v[0:3], v[204:207], v[188:191], v[0:3]
	s_add_i32 s2, s88, 0x100
	s_barrier
	ds_read_b128 v[128:131], v221 offset:32768
	ds_read_b128 v[132:135], v221 offset:33792
	ds_read_b128 v[136:139], v221 offset:34816
	ds_read_b128 v[140:143], v221 offset:35840
	s_add_u32 s0, s76, 0x80000
	s_addc_u32 s1, s77, 0
	s_mov_b32 m0, s37
	ds_read_b128 v[154:157], v163 offset:32768
	ds_read_b128 v[164:167], v163 offset:33792
	ds_read_b128 v[168:171], v163 offset:34816
	ds_read_b128 v[172:175], v163 offset:35840
	ds_read_b128 v[176:179], v163 offset:36864
	ds_read_b128 v[180:183], v163 offset:37888
	ds_read_b128 v[184:187], v163 offset:38912
	ds_read_b128 v[188:191], v163 offset:39936
	global_load_lds_dwordx4 v148, s[0:1]
	s_mov_b32 m0, s38
	s_nop 0
	global_load_lds_dwordx4 v150, s[0:1]
	s_waitcnt lgkmcnt(8)
	s_barrier
	s_waitcnt lgkmcnt(0)
	v_mfma_f32_16x16x32_bf16 v[124:127], v[128:131], v[154:157], v[124:127]
	v_mfma_f32_16x16x32_bf16 v[120:123], v[136:139], v[154:157], v[120:123]
	v_mfma_f32_16x16x32_bf16 v[108:111], v[128:131], v[168:171], v[108:111]
	v_mfma_f32_16x16x32_bf16 v[104:107], v[136:139], v[168:171], v[104:107]
	v_mfma_f32_16x16x32_bf16 v[92:95], v[128:131], v[176:179], v[92:95]
	v_mfma_f32_16x16x32_bf16 v[88:91], v[136:139], v[176:179], v[88:91]
	v_mfma_f32_16x16x32_bf16 v[76:79], v[128:131], v[184:187], v[76:79]
	v_mfma_f32_16x16x32_bf16 v[72:75], v[136:139], v[184:187], v[72:75]
	v_mfma_f32_16x16x32_bf16 v[124:127], v[132:135], v[164:167], v[124:127]
	v_mfma_f32_16x16x32_bf16 v[120:123], v[140:143], v[164:167], v[120:123]
	v_mfma_f32_16x16x32_bf16 v[108:111], v[132:135], v[172:175], v[108:111]
	v_mfma_f32_16x16x32_bf16 v[104:107], v[140:143], v[172:175], v[104:107]
	v_mfma_f32_16x16x32_bf16 v[92:95], v[132:135], v[180:183], v[92:95]
	v_mfma_f32_16x16x32_bf16 v[88:91], v[140:143], v[180:183], v[88:91]
	v_mfma_f32_16x16x32_bf16 v[76:79], v[132:135], v[188:191], v[76:79]
	v_mfma_f32_16x16x32_bf16 v[72:75], v[140:143], v[188:191], v[72:75]
	s_barrier
	s_add_i32 s54, s89, 0x100
	s_add_i32 s0, s2, s14
	ds_read_b128 v[192:195], v221 offset:49152
	ds_read_b128 v[196:199], v221 offset:50176
	ds_read_b128 v[200:203], v221 offset:51200
	ds_read_b128 v[204:207], v221 offset:52224
	s_mov_b32 m0, s0
	s_nop 0
	global_load_lds_dwordx4 v146, s[72:73]
	s_add_i32 m0, s0, 0x2000
	s_nop 0
	global_load_lds_dwordx4 v152, s[72:73]
	s_barrier
	s_waitcnt lgkmcnt(0)
	v_mfma_f32_16x16x32_bf16 v[116:119], v[192:195], v[154:157], v[116:119]
	v_mfma_f32_16x16x32_bf16 v[112:115], v[200:203], v[154:157], v[112:115]
	v_mfma_f32_16x16x32_bf16 v[100:103], v[192:195], v[168:171], v[100:103]
	v_mfma_f32_16x16x32_bf16 v[96:99], v[200:203], v[168:171], v[96:99]
	v_mfma_f32_16x16x32_bf16 v[84:87], v[192:195], v[176:179], v[84:87]
	v_mfma_f32_16x16x32_bf16 v[80:83], v[200:203], v[176:179], v[80:83]
	v_mfma_f32_16x16x32_bf16 v[68:71], v[192:195], v[184:187], v[68:71]
	v_mfma_f32_16x16x32_bf16 v[64:67], v[200:203], v[184:187], v[64:67]
	v_mfma_f32_16x16x32_bf16 v[116:119], v[196:199], v[164:167], v[116:119]
	v_mfma_f32_16x16x32_bf16 v[112:115], v[204:207], v[164:167], v[112:115]
	v_mfma_f32_16x16x32_bf16 v[100:103], v[196:199], v[172:175], v[100:103]
	v_mfma_f32_16x16x32_bf16 v[96:99], v[204:207], v[172:175], v[96:99]
	v_mfma_f32_16x16x32_bf16 v[84:87], v[196:199], v[180:183], v[84:87]
	v_mfma_f32_16x16x32_bf16 v[80:83], v[204:207], v[180:183], v[80:83]
	v_mfma_f32_16x16x32_bf16 v[68:71], v[196:199], v[188:191], v[68:71]
	v_mfma_f32_16x16x32_bf16 v[64:67], v[204:207], v[188:191], v[64:67]
	s_mov_b32 m0, s87
	s_barrier
	ds_read_b128 v[154:157], v163 offset:49152
	ds_read_b128 v[164:167], v163 offset:50176
	ds_read_b128 v[168:171], v163 offset:51200
	ds_read_b128 v[172:175], v163 offset:52224
	ds_read_b128 v[176:179], v163 offset:53248
	ds_read_b128 v[180:183], v163 offset:54272
	ds_read_b128 v[184:187], v163 offset:55296
	ds_read_b128 v[188:191], v163 offset:56320
	global_load_lds_dwordx4 v148, s[74:75]
	s_mov_b32 m0, s94
	s_nop 0
	global_load_lds_dwordx4 v150, s[74:75]
	s_barrier
; #define G_STAGE(bufoff, gbase, voff) do { _Pragma("unroll") for (int _i = 0; _i < 2; ++_i) \
;         __builtin_amdgcn_global_load_lds((const unsigned*)((const char*)(gbase) + (voff)[_i]), (LAS unsigned*)(lds + (bufoff) + ldsw + _i * 8192), 16, 0, 0); } while (0)
; #define G_MMA(ai, bj, At, Bt) do { __builtin_amdgcn_s_setprio(1); _Pragma("unroll") for (int m = 0; m < 4; ++m) _Pragma("unroll") for (int n = 0; n < 2; ++n) _Pragma("unroll") for (int k = 0; k < 2; ++k) \
;         acc[ai][bj][m][n] = __builtin_amdgcn_mfma_f32_16x16x32_bf16(Bt[n][k], At[m][k], acc[ai][bj][m][n], 0, 0, 0); __builtin_amdgcn_s_setprio(0); } while (0)
; #define G_WAIT_V(n) asm volatile("s_waitcnt vmcnt(" #n ")" ::: "memory")
; #define G_WAIT_L(n) asm volatile("s_waitcnt lgkmcnt(" #n ")" ::: "memory")
; #define G_BAR __builtin_amdgcn_s_barrier()
; #define G_SCHED __builtin_amdgcn_sched_barrier(0)
; template <class J>
; DI void gemm_phase(LAS unsigned char* lds, const J& job) {
;     ...
;       G_BAR; G_WAIT_L(0); G_MMA(1, 0, At, B0); G_BAR; G_SCHED;
;       G_STAGE(G_SB(1, 1), b3 + hstepB, voffB);
;       G_WAIT_V(6); G_BAR; G_MMA(1, 1, At, B1); G_BAR;
;   DI void epi(const Acc& acc, const Unit& u, int wr, int wc, int fr, int fq) const {
;     ...
;     for (int ai = 0; ai < 2; ++ai) {
;       f32x4 res[4][2][2];
; #pragma unroll
;       for (int m = 0; m < 4; ++m) {
;         const int row = u.pm * 256 + ai * HALF + wr * 64 + m * 16 + fr;
;         const float* src = (l == 0) ? xp + (size_t)row * DM : out + (size_t)row * DM;
; #pragma unroll
;         for (int bj = 0; bj < 2; ++bj) { const int col = u.pn * 256 + bj * HALF + wc * 32 + 8 * fq; res[m][bj][0] = *(const f32x4*)(src + col); res[m][bj][1] = *(const f32x4*)(src + col + 4); }
;       }
	s_waitcnt lgkmcnt(0)
	v_mfma_f32_16x16x32_bf16 v[60:63], v[128:131], v[154:157], v[60:63]
	v_mfma_f32_16x16x32_bf16 v[56:59], v[136:139], v[154:157], v[56:59]
	v_mfma_f32_16x16x32_bf16 v[44:47], v[128:131], v[168:171], v[44:47]
	v_mfma_f32_16x16x32_bf16 v[40:43], v[136:139], v[168:171], v[40:43]
	v_mfma_f32_16x16x32_bf16 v[28:31], v[128:131], v[176:179], v[28:31]
	v_mfma_f32_16x16x32_bf16 v[24:27], v[136:139], v[176:179], v[24:27]
	v_mfma_f32_16x16x32_bf16 v[20:23], v[128:131], v[184:187], v[20:23]
	v_mfma_f32_16x16x32_bf16 v[12:15], v[136:139], v[184:187], v[12:15]
	v_mfma_f32_16x16x32_bf16 v[60:63], v[132:135], v[164:167], v[60:63]
	v_mfma_f32_16x16x32_bf16 v[56:59], v[140:143], v[164:167], v[56:59]
	v_mfma_f32_16x16x32_bf16 v[44:47], v[132:135], v[172:175], v[44:47]
	v_mfma_f32_16x16x32_bf16 v[40:43], v[140:143], v[172:175], v[40:43]
	v_mfma_f32_16x16x32_bf16 v[28:31], v[132:135], v[180:183], v[28:31]
	v_mfma_f32_16x16x32_bf16 v[24:27], v[140:143], v[180:183], v[24:27]
	v_mfma_f32_16x16x32_bf16 v[20:23], v[132:135], v[188:191], v[20:23]
	v_mfma_f32_16x16x32_bf16 v[12:15], v[140:143], v[188:191], v[12:15]
	s_barrier
	s_add_u32 s0, s72, 0x80000
	s_addc_u32 s1, s73, 0
	s_add_i32 s2, s54, s14
	s_mov_b32 m0, s2
	s_nop 0
	global_load_lds_dwordx4 v146, s[0:1]
	s_add_i32 m0, s2, 0x2000
	s_nop 0
	global_load_lds_dwordx4 v152, s[0:1]
	s_waitcnt vmcnt(6)
	s_barrier
	v_mfma_f32_16x16x32_bf16 v[52:55], v[192:195], v[154:157], v[52:55]
	v_mfma_f32_16x16x32_bf16 v[48:51], v[200:203], v[154:157], v[48:51]
	v_mfma_f32_16x16x32_bf16 v[36:39], v[192:195], v[168:171], v[36:39]
	v_mfma_f32_16x16x32_bf16 v[32:35], v[200:203], v[168:171], v[32:35]
	v_mfma_f32_16x16x32_bf16 v[16:19], v[192:195], v[176:179], v[16:19]
	v_mfma_f32_16x16x32_bf16 v[8:11], v[200:203], v[176:179], v[8:11]
	v_mfma_f32_16x16x32_bf16 v[4:7], v[192:195], v[184:187], v[4:7]
	v_mfma_f32_16x16x32_bf16 v[0:3], v[200:203], v[184:187], v[0:3]
	v_mfma_f32_16x16x32_bf16 v[52:55], v[196:199], v[164:167], v[52:55]
	v_mfma_f32_16x16x32_bf16 v[48:51], v[204:207], v[164:167], v[48:51]
	v_mfma_f32_16x16x32_bf16 v[36:39], v[196:199], v[172:175], v[36:39]
	v_mfma_f32_16x16x32_bf16 v[32:35], v[204:207], v[172:175], v[32:35]
	v_mfma_f32_16x16x32_bf16 v[16:19], v[196:199], v[180:183], v[16:19]
	v_mfma_f32_16x16x32_bf16 v[8:11], v[204:207], v[180:183], v[8:11]
	v_mfma_f32_16x16x32_bf16 v[4:7], v[196:199], v[188:191], v[4:7]
	v_mfma_f32_16x16x32_bf16 v[0:3], v[204:207], v[188:191], v[0:3]
	s_add_i32 s7, s7, 2
	s_addk_i32 s57, 0x100
	s_addk_i32 s44, 0x100
	s_cmp_gt_u32 s7, 29
	s_barrier
	s_cbranch_scc0 .LBB0_42
	s_lshl_b32 s0, s66, 8
	v_mov_b32_e32 v128, v161
	v_mov_b32_e32 v129, v160
	s_add_i32 s0, s0, s67
	s_and_b64 vcc, exec, s[18:19]
	v_add_u32_e32 v156, s0, v129
	s_lshl_b32 s0, s46, 8
	s_or_b32 s0, s0, s83
	v_lshl_add_u32 v128, v128, 3, s0
	v_ashrrev_i32_e32 v157, 31, v156
	v_ashrrev_i32_e32 v129, 31, v128
	v_lshlrev_b64 v[212:213], 13, v[156:157]
	v_lshl_add_u64 v[130:131], s[8:9], 0, v[212:213]
	v_lshlrev_b64 v[154:155], 2, v[128:129]
	v_lshl_add_u64 v[128:129], v[130:131], 0, v[154:155]
	global_load_dwordx4 v[164:167], v[128:129], off offset:16
	global_load_dwordx4 v[168:171], v[128:129], off
	global_load_dwordx4 v[172:175], v[128:129], off offset:528
	global_load_dwordx4 v[176:179], v[128:129], off offset:512
	v_add_u32_e32 v128, 16, v156
	v_ashrrev_i32_e32 v129, 31, v128
	v_lshlrev_b64 v[214:215], 13, v[128:129]
	v_lshl_add_u64 v[128:129], s[8:9], 0, v[214:215]
	v_lshl_add_u64 v[128:129], v[128:129], 0, v[154:155]
	global_load_dwordx4 v[180:183], v[128:129], off offset:16
	global_load_dwordx4 v[184:187], v[128:129], off
	global_load_dwordx4 v[188:191], v[128:129], off offset:528
	global_load_dwordx4 v[192:195], v[128:129], off offset:512
	v_add_u32_e32 v128, 32, v156
	v_ashrrev_i32_e32 v129, 31, v128
	v_lshlrev_b64 v[216:217], 13, v[128:129]
	v_lshl_add_u64 v[128:129], s[8:9], 0, v[216:217]
	v_lshl_add_u64 v[128:129], v[128:129], 0, v[154:155]
	global_load_dwordx4 v[196:199], v[128:129], off offset:16
	global_load_dwordx4 v[200:203], v[128:129], off
	global_load_dwordx4 v[204:207], v[128:129], off offset:528
	global_load_dwordx4 v[208:211], v[128:129], off offset:512
	v_add_u32_e32 v128, 48, v156
	v_ashrrev_i32_e32 v129, 31, v128
	v_lshlrev_b64 v[158:159], 13, v[128:129]
	v_lshl_add_u64 v[128:129], s[8:9], 0, v[158:159]
	v_lshl_add_u64 v[136:137], v[128:129], 0, v[154:155]
	global_load_dwordx4 v[132:135], v[136:137], off offset:16
	global_load_dwordx4 v[140:143], v[136:137], off
	global_load_dwordx4 v[128:131], v[136:137], off offset:528
	s_nop 0
	global_load_dwordx4 v[136:139], v[136:137], off offset:512
	v_lshl_add_u64 v[212:213], s[16:17], 0, v[212:213]
	s_mov_b32 s46, s22
	s_mov_b32 s66, s20
	s_mov_b64 s[68:69], s[64:65]
	s_mov_b64 s[70:71], s[62:63]
	s_movk_i32 s54, 0x4000
	s_movk_i32 s55, 0x6000
	v_readlane_b32 s0, v255, 23
	s_cmpk_gt_u32 s0, 0xff
	s_cbranch_scc1 .Lds_out_x
	s_barrier

;     u.pn = ((((u.pn >> 2) + (c & 7)) & 7) << 2) + (u.pn & 3);
;     return true; }
.LBB0_67:
	v_add_u32_e32 v204, 0x10100, v248
	s_add_i32 s87, s87, 1
	s_mul_i32 s6, s87, s42
	s_add_i32 s6, s6, s43
	s_cmpk_lt_i32 s6, 0x800
	s_cselect_b64 s[70:71], -1, 0
	s_cmpk_gt_i32 s6, 0x7ff
	s_cselect_b64 s[8:9], -1, 0
	s_and_b64 vcc, exec, s[8:9]
	s_cbranch_vccnz .LBB0_73
	s_ashr_i32 s0, s6, 31
	s_lshr_b32 s0, s0, 29
	s_add_i32 s5, s6, s0
	s_and_b32 s0, s5, -8
	s_sub_i32 s6, s6, s0
	s_cmp_gt_i32 s6, -1
	s_mov_b64 s[18:19], -1
	s_cbranch_scc0 .LBB0_70
	s_lshl_b32 s7, s6, 8
	s_mov_b64 s[18:19], 0

; #define G_STAGE(bufoff, gbase, voff) do { _Pragma("unroll") for (int _i = 0; _i < 2; ++_i) \
;         __builtin_amdgcn_global_load_lds((const unsigned*)((const char*)(gbase) + (voff)[_i]), (LAS unsigned*)(lds + (bufoff) + ldsw + _i * 8192), 16, 0, 0); } while (0)
; #define G_LDA(dst, b, h) do { _Pragma("unroll") for (int m = 0; m < 4; ++m) _Pragma("unroll") for (int k = 0; k < 2; ++k) dst[m][k] = *(const LAS bf16x8*)(lds + G_SA(b, h) + aoff + m * 2048 + k * 1024); } while (0)
; #define G_LDB(dst, b, h) do { _Pragma("unroll") for (int n = 0; n < 2; ++n) _Pragma("unroll") for (int k = 0; k < 2; ++k) dst[n][k] = *(const LAS bf16x8*)(lds + G_SB(b, h) + boff + n * 2048 + k * 1024); } while (0)
; #define G_MMA(ai, bj, At, Bt) do { __builtin_amdgcn_s_setprio(1); _Pragma("unroll") for (int m = 0; m < 4; ++m) _Pragma("unroll") for (int n = 0; n < 2; ++n) _Pragma("unroll") for (int k = 0; k < 2; ++k) \
;         acc[ai][bj][m][n] = __builtin_amdgcn_mfma_f32_16x16x32_bf16(Bt[n][k], At[m][k], acc[ai][bj][m][n], 0, 0, 0); __builtin_amdgcn_s_setprio(0); } while (0)
; #define G_WAIT_L(n) asm volatile("s_waitcnt lgkmcnt(" #n ")" ::: "memory")
; #define G_BAR __builtin_amdgcn_s_barrier()
; #define G_SCHED __builtin_amdgcn_sched_barrier(0)
; template <class J>
; DI void gemm_phase(LAS unsigned char* lds, const J& job) {
;     ...
;       const bool last = (t == nt - 2);
;       const char* a1 = cA + G_KT(t + 1);
;       const char* a2 = last ? nA + G_KT(0) : cA + G_KT(t + 2); const char* b2 = last ? nB + G_KT(0) : cB + G_KT(t + 2);
;       const char* a3 = last ? nA + G_KT(1) : cA + G_KT(t + 3); const char* b3 = last ? nB + G_KT(1) : cB + G_KT(t + 3);
;       G_LDB(B0, 0, 0); G_SCHED; G_LDA(At, 0, 0); G_STAGE(G_SA(1, 1), a1 + hstepA, voffA);
;       G_WAIT_L(8); G_BAR; G_WAIT_L(0); G_MMA(0, 0, At, B0); G_BAR; G_SCHED;
;       G_LDB(B1, 0, 1); G_STAGE(G_SB(0, 0), b2, voffB);
;       G_BAR; G_WAIT_L(0); G_MMA(0, 1, At, B1); G_BAR;
;       G_LDA(At, 0, 1); G_STAGE(G_SA(0, 0), a2, voffA);
;       G_BAR; G_WAIT_L(0); G_MMA(1, 0, At, B0); G_BAR; G_SCHED;
.LBB0_74:
	s_add_i32 s1, s56, 0xffffff80
	s_and_b32 s0, s7, 0xf80
	s_and_b32 s1, s1, 0xf00
	s_add_u32 s57, s68, s1
	s_addc_u32 s70, s69, 0
	s_add_u32 s1, s66, s1
	s_addc_u32 s71, s67, 0
	s_and_b32 s72, s56, 0xf80
	s_add_u32 s80, s68, s72
	s_addc_u32 s73, s69, 0
	s_add_u32 s38, s66, s72
	s_addc_u32 s2, s67, 0
	s_cmp_eq_u32 s6, 28
	s_cselect_b32 s75, s46, s70
	s_cselect_b32 s74, s45, s57
	s_cselect_b32 s77, vcc_lo, s71
	s_cselect_b32 s76, s47, s1
	s_cselect_b32 s73, s97, s73
	s_cselect_b32 s72, s33, s80
	s_cselect_b32 s71, s5, s2
	s_cselect_b32 s70, vcc_hi, s38
	s_add_i32 s2, s84, 0x100
	ds_read_b128 v[84:87], v204
	ds_read_b128 v[88:91], v204 offset:1024
	ds_read_b128 v[96:99], v204 offset:2048
	ds_read_b128 v[100:103], v204 offset:3072
	s_add_u32 s0, s19, s0
	s_addc_u32 s1, s21, 0
	s_add_i32 m0, s14, 0xc000
	ds_read_b128 v[154:157], v249
	ds_read_b128 v[158:161], v249 offset:1024
	ds_read_b128 v[162:165], v249 offset:2048
	ds_read_b128 v[166:169], v249 offset:3072
	ds_read_b128 v[170:173], v249 offset:4096
	ds_read_b128 v[174:177], v249 offset:5120
	ds_read_b128 v[178:181], v249 offset:6144
	ds_read_b128 v[182:185], v249 offset:7168
	global_load_lds_dwordx4 v148, s[0:1]
	s_add_i32 m0, s14, 0xe000
	s_nop 0
	global_load_lds_dwordx4 v150, s[0:1]
	s_waitcnt lgkmcnt(8)
	s_barrier
	s_waitcnt lgkmcnt(0)
	v_mfma_f32_16x16x32_bf16 v[140:143], v[84:87], v[154:157], v[140:143]
	v_mfma_f32_16x16x32_bf16 v[136:139], v[96:99], v[154:157], v[136:139]
	v_mfma_f32_16x16x32_bf16 v[124:127], v[84:87], v[162:165], v[124:127]
	v_mfma_f32_16x16x32_bf16 v[120:123], v[96:99], v[162:165], v[120:123]
	v_mfma_f32_16x16x32_bf16 v[108:111], v[84:87], v[170:173], v[108:111]
	v_mfma_f32_16x16x32_bf16 v[104:107], v[96:99], v[170:173], v[104:107]
	v_mfma_f32_16x16x32_bf16 v[76:79], v[84:87], v[178:181], v[76:79]
	v_mfma_f32_16x16x32_bf16 v[72:75], v[96:99], v[178:181], v[72:75]
	v_mfma_f32_16x16x32_bf16 v[140:143], v[88:91], v[158:161], v[140:143]
	v_mfma_f32_16x16x32_bf16 v[136:139], v[100:103], v[158:161], v[136:139]
	v_mfma_f32_16x16x32_bf16 v[124:127], v[88:91], v[166:169], v[124:127]
	v_mfma_f32_16x16x32_bf16 v[120:123], v[100:103], v[166:169], v[120:123]
	v_mfma_f32_16x16x32_bf16 v[108:111], v[88:91], v[174:177], v[108:111]
	v_mfma_f32_16x16x32_bf16 v[104:107], v[100:103], v[174:177], v[104:107]
	v_mfma_f32_16x16x32_bf16 v[76:79], v[88:91], v[182:185], v[76:79]
	v_mfma_f32_16x16x32_bf16 v[72:75], v[100:103], v[182:185], v[72:75]
	s_barrier
	s_add_i32 s38, s85, 0x100
	s_add_i32 s0, s2, s78
	s_mov_b32 m0, s0
	ds_read_b128 v[186:189], v204 offset:16384
	ds_read_b128 v[190:193], v204 offset:17408
	ds_read_b128 v[194:197], v204 offset:18432
	ds_read_b128 v[198:201], v204 offset:19456
	global_load_lds_dwordx4 v146, s[76:77]
	s_add_i32 m0, s0, 0x2000
	s_nop 0
	global_load_lds_dwordx4 v152, s[76:77]
	s_barrier
	s_waitcnt lgkmcnt(0)
	v_mfma_f32_16x16x32_bf16 v[132:135], v[186:189], v[154:157], v[132:135]
	v_mfma_f32_16x16x32_bf16 v[128:131], v[194:197], v[154:157], v[128:131]
	v_mfma_f32_16x16x32_bf16 v[116:119], v[186:189], v[162:165], v[116:119]
	v_mfma_f32_16x16x32_bf16 v[112:115], v[194:197], v[162:165], v[112:115]
	v_mfma_f32_16x16x32_bf16 v[92:95], v[186:189], v[170:173], v[92:95]
	v_mfma_f32_16x16x32_bf16 v[80:83], v[194:197], v[170:173], v[80:83]
	v_mfma_f32_16x16x32_bf16 v[68:71], v[186:189], v[178:181], v[68:71]
	v_mfma_f32_16x16x32_bf16 v[64:67], v[194:197], v[178:181], v[64:67]
	v_mfma_f32_16x16x32_bf16 v[132:135], v[190:193], v[158:161], v[132:135]
	v_mfma_f32_16x16x32_bf16 v[128:131], v[198:201], v[158:161], v[128:131]
	v_mfma_f32_16x16x32_bf16 v[116:119], v[190:193], v[166:169], v[116:119]
	v_mfma_f32_16x16x32_bf16 v[112:115], v[198:201], v[166:169], v[112:115]
	v_mfma_f32_16x16x32_bf16 v[92:95], v[190:193], v[174:177], v[92:95]
	v_mfma_f32_16x16x32_bf16 v[80:83], v[198:201], v[174:177], v[80:83]
	v_mfma_f32_16x16x32_bf16 v[68:71], v[190:193], v[182:185], v[68:71]
	v_mfma_f32_16x16x32_bf16 v[64:67], v[198:201], v[182:185], v[64:67]
	s_mov_b32 m0, s14
	s_barrier
	ds_read_b128 v[154:157], v249 offset:16384
	ds_read_b128 v[158:161], v249 offset:17408
	ds_read_b128 v[162:165], v249 offset:18432
	ds_read_b128 v[166:169], v249 offset:19456
	ds_read_b128 v[170:173], v249 offset:20480
	ds_read_b128 v[174:177], v249 offset:21504
	ds_read_b128 v[178:181], v249 offset:22528
	ds_read_b128 v[182:185], v249 offset:23552
	global_load_lds_dwordx4 v148, s[74:75]
	s_mov_b32 m0, s15
	s_nop 0
	global_load_lds_dwordx4 v150, s[74:75]
	s_barrier
	s_waitcnt lgkmcnt(0)
	v_mfma_f32_16x16x32_bf16 v[60:63], v[84:87], v[154:157], v[60:63]
	v_mfma_f32_16x16x32_bf16 v[56:59], v[96:99], v[154:157], v[56:59]
	v_mfma_f32_16x16x32_bf16 v[44:47], v[84:87], v[162:165], v[44:47]
	v_mfma_f32_16x16x32_bf16 v[40:43], v[96:99], v[162:165], v[40:43]
	v_mfma_f32_16x16x32_bf16 v[28:31], v[84:87], v[170:173], v[28:31]
	v_mfma_f32_16x16x32_bf16 v[24:27], v[96:99], v[170:173], v[24:27]
	v_mfma_f32_16x16x32_bf16 v[12:15], v[84:87], v[178:181], v[12:15]
	v_mfma_f32_16x16x32_bf16 v[8:11], v[96:99], v[178:181], v[8:11]
	v_mfma_f32_16x16x32_bf16 v[60:63], v[88:91], v[158:161], v[60:63]
	v_mfma_f32_16x16x32_bf16 v[56:59], v[100:103], v[158:161], v[56:59]
	v_mfma_f32_16x16x32_bf16 v[44:47], v[88:91], v[166:169], v[44:47]
	v_mfma_f32_16x16x32_bf16 v[40:43], v[100:103], v[166:169], v[40:43]
	v_mfma_f32_16x16x32_bf16 v[28:31], v[88:91], v[174:177], v[28:31]
	v_mfma_f32_16x16x32_bf16 v[24:27], v[100:103], v[174:177], v[24:27]
	v_mfma_f32_16x16x32_bf16 v[12:15], v[88:91], v[182:185], v[12:15]
	v_mfma_f32_16x16x32_bf16 v[8:11], v[100:103], v[182:185], v[8:11]
	s_barrier
; #define G_STAGE(bufoff, gbase, voff) do { _Pragma("unroll") for (int _i = 0; _i < 2; ++_i) \
;         __builtin_amdgcn_global_load_lds((const unsigned*)((const char*)(gbase) + (voff)[_i]), (LAS unsigned*)(lds + (bufoff) + ldsw + _i * 8192), 16, 0, 0); } while (0)
; #define G_LDA(dst, b, h) do { _Pragma("unroll") for (int m = 0; m < 4; ++m) _Pragma("unroll") for (int k = 0; k < 2; ++k) dst[m][k] = *(const LAS bf16x8*)(lds + G_SA(b, h) + aoff + m * 2048 + k * 1024); } while (0)
; #define G_LDB(dst, b, h) do { _Pragma("unroll") for (int n = 0; n < 2; ++n) _Pragma("unroll") for (int k = 0; k < 2; ++k) dst[n][k] = *(const LAS bf16x8*)(lds + G_SB(b, h) + boff + n * 2048 + k * 1024); } while (0)
; #define G_MMA(ai, bj, At, Bt) do { __builtin_amdgcn_s_setprio(1); _Pragma("unroll") for (int m = 0; m < 4; ++m) _Pragma("unroll") for (int n = 0; n < 2; ++n) _Pragma("unroll") for (int k = 0; k < 2; ++k) \
;         acc[ai][bj][m][n] = __builtin_amdgcn_mfma_f32_16x16x32_bf16(Bt[n][k], At[m][k], acc[ai][bj][m][n], 0, 0, 0); __builtin_amdgcn_s_setprio(0); } while (0)
; #define G_WAIT_V(n) asm volatile("s_waitcnt vmcnt(" #n ")" ::: "memory")
; #define G_WAIT_L(n) asm volatile("s_waitcnt lgkmcnt(" #n ")" ::: "memory")
; #define G_BAR __builtin_amdgcn_s_barrier()
; #define G_SCHED __builtin_amdgcn_sched_barrier(0)
; template <class J>
; DI void gemm_phase(LAS unsigned char* lds, const J& job) {
;     ...
;       G_STAGE(G_SB(0, 1), b2 + hstepB, voffB);
;       G_WAIT_V(6); G_BAR; G_MMA(1, 1, At, B1); G_BAR;
;       G_LDB(B0, 1, 0); G_SCHED; G_LDA(At, 1, 0); G_STAGE(G_SA(0, 1), a2 + hstepA, voffA);
;       G_WAIT_L(8); G_BAR; G_WAIT_L(0); G_MMA(0, 0, At, B0); G_BAR; G_SCHED;
;       G_LDB(B1, 1, 1); G_STAGE(G_SB(1, 0), b3, voffB);
;       G_BAR; G_WAIT_L(0); G_MMA(0, 1, At, B1); G_BAR;
;       G_LDA(At, 1, 1); G_STAGE(G_SA(1, 0), a3, voffA);
	s_add_u32 s0, s76, 0x1000000
	s_addc_u32 s1, s77, 0
	s_add_i32 s2, s38, s78
	s_mov_b32 m0, s2
	s_nop 0
	global_load_lds_dwordx4 v146, s[0:1]
	s_add_i32 m0, s2, 0x2000
	s_nop 0
	global_load_lds_dwordx4 v152, s[0:1]
	s_waitcnt vmcnt(6)
	s_barrier
	v_mfma_f32_16x16x32_bf16 v[52:55], v[186:189], v[154:157], v[52:55]
	v_mfma_f32_16x16x32_bf16 v[48:51], v[194:197], v[154:157], v[48:51]
	v_mfma_f32_16x16x32_bf16 v[36:39], v[186:189], v[162:165], v[36:39]
	v_mfma_f32_16x16x32_bf16 v[32:35], v[194:197], v[162:165], v[32:35]
	v_mfma_f32_16x16x32_bf16 v[20:23], v[186:189], v[170:173], v[20:23]
	v_mfma_f32_16x16x32_bf16 v[16:19], v[194:197], v[170:173], v[16:19]
	v_mfma_f32_16x16x32_bf16 v[4:7], v[186:189], v[178:181], v[4:7]
	v_mfma_f32_16x16x32_bf16 v[0:3], v[194:197], v[178:181], v[0:3]
	v_mfma_f32_16x16x32_bf16 v[52:55], v[190:193], v[158:161], v[52:55]
	v_mfma_f32_16x16x32_bf16 v[48:51], v[198:201], v[158:161], v[48:51]
	v_mfma_f32_16x16x32_bf16 v[36:39], v[190:193], v[166:169], v[36:39]
	v_mfma_f32_16x16x32_bf16 v[32:35], v[198:201], v[166:169], v[32:35]
	v_mfma_f32_16x16x32_bf16 v[20:23], v[190:193], v[174:177], v[20:23]
	v_mfma_f32_16x16x32_bf16 v[16:19], v[198:201], v[174:177], v[16:19]
	v_mfma_f32_16x16x32_bf16 v[4:7], v[190:193], v[182:185], v[4:7]
	v_mfma_f32_16x16x32_bf16 v[0:3], v[198:201], v[182:185], v[0:3]
	s_add_i32 s2, s88, 0x100
	s_barrier
	ds_read_b128 v[84:87], v204 offset:32768
	ds_read_b128 v[88:91], v204 offset:33792
	ds_read_b128 v[96:99], v204 offset:34816
	ds_read_b128 v[100:103], v204 offset:35840
	s_add_u32 s0, s74, 0x80000
	s_addc_u32 s1, s75, 0
	s_mov_b32 m0, s83
	ds_read_b128 v[154:157], v249 offset:32768
	ds_read_b128 v[158:161], v249 offset:33792
	ds_read_b128 v[162:165], v249 offset:34816
	ds_read_b128 v[166:169], v249 offset:35840
	ds_read_b128 v[170:173], v249 offset:36864
	ds_read_b128 v[174:177], v249 offset:37888
	ds_read_b128 v[178:181], v249 offset:38912
	ds_read_b128 v[182:185], v249 offset:39936
	global_load_lds_dwordx4 v148, s[0:1]
	s_mov_b32 m0, s36
	s_nop 0
	global_load_lds_dwordx4 v150, s[0:1]
	s_waitcnt lgkmcnt(8)
	s_barrier
	s_waitcnt lgkmcnt(0)
	v_mfma_f32_16x16x32_bf16 v[140:143], v[84:87], v[154:157], v[140:143]
	v_mfma_f32_16x16x32_bf16 v[136:139], v[96:99], v[154:157], v[136:139]
	v_mfma_f32_16x16x32_bf16 v[124:127], v[84:87], v[162:165], v[124:127]
	v_mfma_f32_16x16x32_bf16 v[120:123], v[96:99], v[162:165], v[120:123]
	v_mfma_f32_16x16x32_bf16 v[108:111], v[84:87], v[170:173], v[108:111]
	v_mfma_f32_16x16x32_bf16 v[104:107], v[96:99], v[170:173], v[104:107]
	v_mfma_f32_16x16x32_bf16 v[76:79], v[84:87], v[178:181], v[76:79]
	v_mfma_f32_16x16x32_bf16 v[72:75], v[96:99], v[178:181], v[72:75]
	v_mfma_f32_16x16x32_bf16 v[140:143], v[88:91], v[158:161], v[140:143]
	v_mfma_f32_16x16x32_bf16 v[136:139], v[100:103], v[158:161], v[136:139]
	v_mfma_f32_16x16x32_bf16 v[124:127], v[88:91], v[166:169], v[124:127]
	v_mfma_f32_16x16x32_bf16 v[120:123], v[100:103], v[166:169], v[120:123]
	v_mfma_f32_16x16x32_bf16 v[108:111], v[88:91], v[174:177], v[108:111]
	v_mfma_f32_16x16x32_bf16 v[104:107], v[100:103], v[174:177], v[104:107]
	v_mfma_f32_16x16x32_bf16 v[76:79], v[88:91], v[182:185], v[76:79]
	v_mfma_f32_16x16x32_bf16 v[72:75], v[100:103], v[182:185], v[72:75]
	s_barrier
	s_add_i32 s38, s89, 0x100
	s_add_i32 s0, s2, s78
	s_mov_b32 m0, s0
	ds_read_b128 v[186:189], v204 offset:49152
	ds_read_b128 v[190:193], v204 offset:50176
	ds_read_b128 v[194:197], v204 offset:51200
	ds_read_b128 v[198:201], v204 offset:52224
	global_load_lds_dwordx4 v146, s[70:71]
	s_add_i32 m0, s0, 0x2000
	s_nop 0
	global_load_lds_dwordx4 v152, s[70:71]
	s_barrier
	s_waitcnt lgkmcnt(0)
	v_mfma_f32_16x16x32_bf16 v[132:135], v[186:189], v[154:157], v[132:135]
	v_mfma_f32_16x16x32_bf16 v[128:131], v[194:197], v[154:157], v[128:131]
	v_mfma_f32_16x16x32_bf16 v[116:119], v[186:189], v[162:165], v[116:119]
	v_mfma_f32_16x16x32_bf16 v[112:115], v[194:197], v[162:165], v[112:115]
	v_mfma_f32_16x16x32_bf16 v[92:95], v[186:189], v[170:173], v[92:95]
	v_mfma_f32_16x16x32_bf16 v[80:83], v[194:197], v[170:173], v[80:83]
	v_mfma_f32_16x16x32_bf16 v[68:71], v[186:189], v[178:181], v[68:71]
	v_mfma_f32_16x16x32_bf16 v[64:67], v[194:197], v[178:181], v[64:67]
	v_mfma_f32_16x16x32_bf16 v[132:135], v[190:193], v[158:161], v[132:135]
	v_mfma_f32_16x16x32_bf16 v[128:131], v[198:201], v[158:161], v[128:131]
	v_mfma_f32_16x16x32_bf16 v[116:119], v[190:193], v[166:169], v[116:119]
	v_mfma_f32_16x16x32_bf16 v[112:115], v[198:201], v[166:169], v[112:115]
	v_mfma_f32_16x16x32_bf16 v[92:95], v[190:193], v[174:177], v[92:95]
	v_mfma_f32_16x16x32_bf16 v[80:83], v[198:201], v[174:177], v[80:83]
	v_mfma_f32_16x16x32_bf16 v[68:71], v[190:193], v[182:185], v[68:71]
	v_mfma_f32_16x16x32_bf16 v[64:67], v[198:201], v[182:185], v[64:67]
	s_mov_b32 m0, s24
	s_barrier
	ds_read_b128 v[154:157], v249 offset:49152
	ds_read_b128 v[158:161], v249 offset:50176
	ds_read_b128 v[162:165], v249 offset:51200
	ds_read_b128 v[166:169], v249 offset:52224
	ds_read_b128 v[170:173], v249 offset:53248
	ds_read_b128 v[174:177], v249 offset:54272
	ds_read_b128 v[178:181], v249 offset:55296
	ds_read_b128 v[182:185], v249 offset:56320
	global_load_lds_dwordx4 v148, s[72:73]
	s_mov_b32 m0, s25
	s_nop 0
	global_load_lds_dwordx4 v150, s[72:73]
	s_barrier
; #define G_STAGE(bufoff, gbase, voff) do { _Pragma("unroll") for (int _i = 0; _i < 2; ++_i) \
;         __builtin_amdgcn_global_load_lds((const unsigned*)((const char*)(gbase) + (voff)[_i]), (LAS unsigned*)(lds + (bufoff) + ldsw + _i * 8192), 16, 0, 0); } while (0)
; #define G_MMA(ai, bj, At, Bt) do { __builtin_amdgcn_s_setprio(1); _Pragma("unroll") for (int m = 0; m < 4; ++m) _Pragma("unroll") for (int n = 0; n < 2; ++n) _Pragma("unroll") for (int k = 0; k < 2; ++k) \
;         acc[ai][bj][m][n] = __builtin_amdgcn_mfma_f32_16x16x32_bf16(Bt[n][k], At[m][k], acc[ai][bj][m][n], 0, 0, 0); __builtin_amdgcn_s_setprio(0); } while (0)
; #define G_WAIT_V(n) asm volatile("s_waitcnt vmcnt(" #n ")" ::: "memory")
; #define G_WAIT_L(n) asm volatile("s_waitcnt lgkmcnt(" #n ")" ::: "memory")
; #define G_BAR __builtin_amdgcn_s_barrier()
; #define G_SCHED __builtin_amdgcn_sched_barrier(0)
; template <class J>
; DI void gemm_phase(LAS unsigned char* lds, const J& job) {
;     ...
;       G_BAR; G_WAIT_L(0); G_MMA(1, 0, At, B0); G_BAR; G_SCHED;
;       G_STAGE(G_SB(1, 1), b3 + hstepB, voffB);
;       G_WAIT_V(6); G_BAR; G_MMA(1, 1, At, B1); G_BAR;
	s_waitcnt lgkmcnt(0)
	v_mfma_f32_16x16x32_bf16 v[60:63], v[84:87], v[154:157], v[60:63]
	v_mfma_f32_16x16x32_bf16 v[56:59], v[96:99], v[154:157], v[56:59]
	v_mfma_f32_16x16x32_bf16 v[44:47], v[84:87], v[162:165], v[44:47]
	v_mfma_f32_16x16x32_bf16 v[40:43], v[96:99], v[162:165], v[40:43]
	v_mfma_f32_16x16x32_bf16 v[28:31], v[84:87], v[170:173], v[28:31]
	v_mfma_f32_16x16x32_bf16 v[24:27], v[96:99], v[170:173], v[24:27]
	v_mfma_f32_16x16x32_bf16 v[12:15], v[84:87], v[178:181], v[12:15]
	v_mfma_f32_16x16x32_bf16 v[8:11], v[96:99], v[178:181], v[8:11]
	v_mfma_f32_16x16x32_bf16 v[60:63], v[88:91], v[158:161], v[60:63]
	v_mfma_f32_16x16x32_bf16 v[56:59], v[100:103], v[158:161], v[56:59]
	v_mfma_f32_16x16x32_bf16 v[44:47], v[88:91], v[166:169], v[44:47]
	v_mfma_f32_16x16x32_bf16 v[40:43], v[100:103], v[166:169], v[40:43]
	v_mfma_f32_16x16x32_bf16 v[28:31], v[88:91], v[174:177], v[28:31]
	v_mfma_f32_16x16x32_bf16 v[24:27], v[100:103], v[174:177], v[24:27]
	v_mfma_f32_16x16x32_bf16 v[12:15], v[88:91], v[182:185], v[12:15]
	v_mfma_f32_16x16x32_bf16 v[8:11], v[100:103], v[182:185], v[8:11]
	s_barrier
	s_add_u32 s0, s70, 0x1000000
	s_addc_u32 s1, s71, 0
	s_add_i32 s2, s38, s78
	s_mov_b32 m0, s2
	s_nop 0
	global_load_lds_dwordx4 v146, s[0:1]
	s_add_i32 m0, s2, 0x2000
	s_nop 0
	global_load_lds_dwordx4 v152, s[0:1]
	s_waitcnt vmcnt(6)
	s_barrier
	v_mfma_f32_16x16x32_bf16 v[52:55], v[186:189], v[154:157], v[52:55]
	v_mfma_f32_16x16x32_bf16 v[48:51], v[194:197], v[154:157], v[48:51]
	v_mfma_f32_16x16x32_bf16 v[36:39], v[186:189], v[162:165], v[36:39]
	v_mfma_f32_16x16x32_bf16 v[32:35], v[194:197], v[162:165], v[32:35]
	v_mfma_f32_16x16x32_bf16 v[20:23], v[186:189], v[170:173], v[20:23]
	v_mfma_f32_16x16x32_bf16 v[16:19], v[194:197], v[170:173], v[16:19]
	v_mfma_f32_16x16x32_bf16 v[4:7], v[186:189], v[178:181], v[4:7]
	v_mfma_f32_16x16x32_bf16 v[0:3], v[194:197], v[178:181], v[0:3]
	v_mfma_f32_16x16x32_bf16 v[52:55], v[190:193], v[158:161], v[52:55]
	v_mfma_f32_16x16x32_bf16 v[48:51], v[198:201], v[158:161], v[48:51]
	v_mfma_f32_16x16x32_bf16 v[36:39], v[190:193], v[166:169], v[36:39]
	v_mfma_f32_16x16x32_bf16 v[32:35], v[198:201], v[166:169], v[32:35]
	v_mfma_f32_16x16x32_bf16 v[20:23], v[190:193], v[174:177], v[20:23]
	v_mfma_f32_16x16x32_bf16 v[16:19], v[198:201], v[174:177], v[16:19]
	v_mfma_f32_16x16x32_bf16 v[4:7], v[190:193], v[182:185], v[4:7]
	v_mfma_f32_16x16x32_bf16 v[0:3], v[198:201], v[182:185], v[0:3]
	s_add_i32 s6, s6, 2
	s_addk_i32 s56, 0x100
	s_addk_i32 s7, 0x100
	s_cmp_gt_u32 s6, 29
	s_barrier
	s_cbranch_scc0 .LBB0_74
;   DI void epi(const Acc& acc, const Unit& u, int wr, int wc, int fr, int fq) const {
;     const int cc = u.pn * 64 + 16 * wc + 4 * fq;
;     u32x2 zz[2][4][4];
; #pragma unroll
;     for (int ai = 0; ai < 2; ++ai)
; #pragma unroll
;       for (int m = 0; m < 4; ++m) {
;         const u16* zr = Z + (size_t)(u.pm * 256 + ai * HALF + wr * 64 + m * 16 + fr) * NGATE + cc;
; #pragma unroll
;         for (int br = 0; br < 4; ++br) zz[ai][m][br] = *(const u32x2*)(zr + br * 2048);
;       }
;     f32x4 bg[4];
; #pragma unroll
;     for (int br = 0; br < 4; ++br) bg[br] = *(const f32x4*)(bgate + br * 2048 + cc);
	v_mov_b32_e32 v84, v247
	v_mov_b32_e32 v85, v246
	s_lshl_b32 s0, s44, 6
	s_or_b32 s0, s0, s96
	v_lshl_add_u32 v84, v84, 2, s0
	s_lshl_b32 s0, s64, 8
	s_add_i32 s0, s0, s37
	v_add_u32_e32 v224, s0, v85
	v_ashrrev_i32_e32 v85, 31, v84
	v_lshlrev_b64 v[154:155], 1, v[84:85]
	v_ashrrev_i32_e32 v225, 31, v224
	v_lshl_add_u64 v[86:87], s[26:27], 0, v[154:155]
	v_lshlrev_b64 v[88:89], 14, v[224:225]
	v_lshl_add_u64 v[88:89], v[86:87], 0, v[88:89]
	v_add_co_u32_e32 v90, vcc, s82, v88
	v_add_u32_e32 v212, 16, v224
	s_nop 0
	v_addc_co_u32_e32 v91, vcc, 0, v89, vcc
	v_ashrrev_i32_e32 v213, 31, v212
	v_add_co_u32_e32 v96, vcc, s92, v88
	v_lshlrev_b64 v[98:99], 14, v[212:213]
	s_nop 0
	v_addc_co_u32_e32 v97, vcc, 0, v89, vcc
	v_lshl_add_u64 v[98:99], v[86:87], 0, v[98:99]
	v_add_co_u32_e32 v100, vcc, s82, v98
	v_add_u32_e32 v202, 32, v224
	s_nop 0
	v_addc_co_u32_e32 v101, vcc, 0, v99, vcc
	global_load_dwordx2 v[230:231], v[90:91], off offset:-4096
	global_load_dwordx2 v[226:227], v[90:91], off
	global_load_dwordx2 v[220:221], v[100:101], off offset:-4096
	global_load_dwordx2 v[214:215], v[100:101], off
	v_add_co_u32_e32 v90, vcc, s92, v98
	v_ashrrev_i32_e32 v203, 31, v202
	s_nop 0
	v_addc_co_u32_e32 v91, vcc, 0, v99, vcc
	global_load_dwordx2 v[232:233], v[88:89], off
	global_load_dwordx2 v[228:229], v[96:97], off
	global_load_dwordx2 v[222:223], v[98:99], off
	global_load_dwordx2 v[216:217], v[90:91], off
	v_lshlrev_b64 v[88:89], 14, v[202:203]
	v_lshl_add_u64 v[88:89], v[86:87], 0, v[88:89]
	v_add_co_u32_e32 v90, vcc, s82, v88
	v_add_u32_e32 v190, 48, v224
	s_nop 0
	v_addc_co_u32_e32 v91, vcc, 0, v89, vcc
	v_ashrrev_i32_e32 v191, 31, v190
	v_add_co_u32_e32 v96, vcc, s92, v88
	v_lshlrev_b64 v[98:99], 14, v[190:191]
	s_nop 0
	v_addc_co_u32_e32 v97, vcc, 0, v89, vcc
	v_lshl_add_u64 v[98:99], v[86:87], 0, v[98:99]
	v_add_co_u32_e32 v100, vcc, s82, v98
	v_add_u32_e32 v184, 0x80, v224
	s_nop 0
	v_addc_co_u32_e32 v101, vcc, 0, v99, vcc
	global_load_dwordx2 v[210:211], v[90:91], off offset:-4096
	global_load_dwordx2 v[206:207], v[90:91], off
	global_load_dwordx2 v[200:201], v[100:101], off offset:-4096
	global_load_dwordx2 v[192:193], v[100:101], off
	v_add_co_u32_e32 v90, vcc, s92, v98
	v_lshl_add_u64 v[84:85], v[84:85], 2, s[12:13]
	v_ashrrev_i32_e32 v185, 31, v184
	v_addc_co_u32_e32 v91, vcc, 0, v99, vcc
	global_load_dwordx4 v[100:103], v[84:85], off
	global_load_dwordx2 v[218:219], v[88:89], off
	global_load_dwordx2 v[208:209], v[96:97], off
	global_load_dwordx2 v[204:205], v[98:99], off
	global_load_dwordx2 v[198:199], v[90:91], off
	v_lshlrev_b64 v[88:89], 14, v[184:185]
	v_lshl_add_u64 v[88:89], v[86:87], 0, v[88:89]
	v_add_co_u32_e32 v90, vcc, s82, v88
	v_add_u32_e32 v174, 0x90, v224
	s_nop 0
	v_addc_co_u32_e32 v91, vcc, 0, v89, vcc
	v_add_co_u32_e32 v156, vcc, s92, v88
	v_ashrrev_i32_e32 v175, 31, v174
	s_nop 0
	v_addc_co_u32_e32 v157, vcc, 0, v89, vcc
	v_add_co_u32_e32 v96, vcc, s82, v84
	v_lshlrev_b64 v[158:159], 14, v[174:175]
	s_nop 0
	v_addc_co_u32_e32 v97, vcc, 0, v85, vcc
	global_load_dwordx4 v[96:99], v[96:97], off
	v_lshl_add_u64 v[158:159], v[86:87], 0, v[158:159]
	v_add_co_u32_e32 v160, vcc, s82, v158
	v_add_u32_e32 v164, 0xa0, v224
	s_nop 0
	v_addc_co_u32_e32 v161, vcc, 0, v159, vcc
	global_load_dwordx2 v[194:195], v[90:91], off offset:-4096
	global_load_dwordx2 v[186:187], v[90:91], off
	global_load_dwordx2 v[180:181], v[160:161], off offset:-4096
	global_load_dwordx2 v[176:177], v[160:161], off
	v_add_co_u32_e32 v90, vcc, s92, v158
	v_ashrrev_i32_e32 v165, 31, v164
	s_nop 0
	v_addc_co_u32_e32 v91, vcc, 0, v159, vcc
	global_load_dwordx2 v[196:197], v[88:89], off
	global_load_dwordx2 v[188:189], v[156:157], off
	global_load_dwordx2 v[182:183], v[158:159], off
	global_load_dwordx2 v[178:179], v[90:91], off
	v_lshlrev_b64 v[88:89], 14, v[164:165]
	v_lshl_add_u64 v[162:163], v[86:87], 0, v[88:89]
	v_add_co_u32_e32 v158, vcc, s82, v162
	v_add_u32_e32 v156, 0xb0, v224
	s_nop 0
	v_addc_co_u32_e32 v159, vcc, 0, v163, vcc
	v_add_co_u32_e32 v168, vcc, s92, v162
	v_ashrrev_i32_e32 v157, 31, v156
	s_nop 0
	v_addc_co_u32_e32 v169, vcc, 0, v163, vcc
	v_add_co_u32_e32 v88, vcc, s54, v84
	v_lshlrev_b64 v[160:161], 14, v[156:157]
	s_nop 0
	v_addc_co_u32_e32 v89, vcc, 0, v85, vcc
	global_load_dwordx4 v[88:91], v[88:89], off
	v_lshl_add_u64 v[250:251], v[86:87], 0, v[160:161]
	v_add_co_u32_e32 v86, vcc, s82, v250
	s_mov_b32 s44, s20
	s_nop 0
	v_addc_co_u32_e32 v87, vcc, 0, v251, vcc
	v_add_co_u32_e32 v84, vcc, s55, v84
	global_load_dwordx2 v[170:171], v[158:159], off offset:-4096
	global_load_dwordx2 v[166:167], v[158:159], off
	global_load_dwordx2 v[160:161], v[86:87], off offset:-4096
	s_nop 0
	global_load_dwordx2 v[158:159], v[86:87], off
	v_addc_co_u32_e32 v85, vcc, 0, v85, vcc
	global_load_dwordx4 v[84:87], v[84:85], off
	v_add_co_u32_e32 v252, vcc, s92, v250
	s_mov_b32 s64, s18
	s_nop 0
	v_addc_co_u32_e32 v253, vcc, 0, v251, vcc
	s_and_b64 vcc, exec, s[8:9]
	s_mov_b64 s[66:67], s[62:63]
	s_mov_b64 s[68:69], s[22:23]
	v_readlane_b32 s0, v255, 23
	s_cmpk_gt_u32 s0, 0xff
	s_cbranch_scc1 .Lds_gate_x
	s_barrier

; DI int my_block() { int b = blockIdx.x; asm volatile("" : "+s"(b)); return b; }
; #define G_STAGE(bufoff, gbase, voff) do { _Pragma("unroll") for (int _i = 0; _i < 2; ++_i) \
;         __builtin_amdgcn_global_load_lds((const unsigned*)((const char*)(gbase) + (voff)[_i]), (LAS unsigned*)(lds + (bufoff) + ldsw + _i * 8192), 16, 0, 0); } while (0)
; #define G_WAIT_V(n) asm volatile("s_waitcnt vmcnt(" #n ")" ::: "memory")
; #define G_BAR __builtin_amdgcn_s_barrier()
;   DI const char* aptr(const Unit& u) const { return (const char*)(h + (size_t)u.pm * 256 * DM); }
;   DI const char* bptr(const Unit& u) const { return (const char*)(winT + (size_t)u.pn * 256 * DM); }
;   DI bool next(int i, Unit& u) const { const int L = i * G + c; if (L >= nunits) return false; u.kind = 0; decode_unit(L, 65, 32, u.pm, u.pn); return true; }
;   DI const char* aptr(const Unit& u) const { return (const char*)(y + (size_t)u.pm * 256 * DM + (u.pn >> 3) * 512); }
;   DI const char* bptr(const Unit& u) const { return (const char*)(wbT + (size_t)u.pn * 256 * 512); }
;   DI const char* aptr(const Unit& u) const { return (const char*)(h + (size_t)u.pm * 256 * DM); }
;   DI const char* bptr(const Unit& u) const { return (const char*)(wgT + (size_t)u.pn * 64 * DM); }
; template <class J>
; DI void gemm_phase(LAS unsigned char* lds, const J& job) {
;     ...
;   const int aoff = lds_byte(wr * 64 + fr, fq * 8), boff = lds_byte(wc * 32 + fr, fq * 8);
;     ...
;   Unit cur, nxt; int ui = 0;
;   if (!job.next(0, cur)) return;
;   f32x4 acc[2][2][4][2];
; #pragma unroll
;   for (int a = 0; a < 2; ++a)
; #pragma unroll
;     for (int b = 0; b < 2; ++b)
; #pragma unroll
;       for (int m = 0; m < 4; ++m)
; #pragma unroll
;         for (int n = 0; n < 2; ++n) acc[a][b][m][n] = (f32x4){0.f, 0.f, 0.f, 0.f};
;   bf16x8 At[4][2], B0[2][2], B1[2][2];
;   const char* cA = job.aptr(cur); const char* cB = job.bptr(cur);
;   const int koff = (my_block() & 7) * (nt >> 3), kmask = nt - 1;
;     ...
;   G_STAGE(G_SB(0, 0), cB + G_KT(0), voffB); G_STAGE(G_SA(0, 0), cA + G_KT(0), voffA); G_STAGE(G_SB(0, 1), cB + hstepB + G_KT(0), voffB); G_STAGE(G_SA(0, 1), cA + hstepA + G_KT(0), voffA);
;   if (wr == 1) G_BAR;
;   G_WAIT_V(4); G_BAR;
;   G_STAGE(G_SB(1, 0), cB + G_KT(1), voffB); G_STAGE(G_SA(1, 0), cA + G_KT(1), voffA); G_STAGE(G_SB(1, 1), cB + hstepB + G_KT(1), voffB);
;   G_WAIT_V(6); G_BAR;
.LBB0_100:
	v_bfe_u32 v137, v0, 4, 2
	v_and_b32_e32 v136, 15, v0
	v_lshlrev_b32_e32 v1, 4, v137
	v_lshlrev_b32_e32 v0, 2, v0
	v_lshl_or_b32 v1, v136, 6, v1
	s_lshl_b32 s0, s6, 13
	v_and_b32_e32 v0, 32, v0
	v_bitop3_b32 v2, v1, s0, v0 bitop3:0xde
	s_lshl_b32 s0, s5, 5
	s_and_b32 s45, s0, 0x60
	s_lshl_b32 s0, s45, 7
	v_bitop3_b32 v138, v1, s0, v0 bitop3:0xde
	v_add_u32_e32 v208, 0x10100, v138
	s_add_i32 s0, s23, 0x80
	s_lshl_b32 s44, s6, 6
	s_and_b32 s74, s0, 0x380
	s_add_u32 s12, s62, s74
	s_addc_u32 s13, s63, 0
	s_add_i32 m0, s25, 0x18000
	v_lshl_add_u64 v[0:1], s[12:13], 0, v[146:147]
	v_mov_b32_e32 v129, v147
	s_waitcnt vmcnt(4)
	s_barrier
	global_load_lds_dwordx4 v[0:1], off
	s_add_i32 m0, s25, 0x1a000
	v_lshl_add_u64 v[0:1], s[12:13], 0, v[128:129]
	s_add_u32 s12, s64, s74
	v_mov_b32_e32 v133, v147
	s_addc_u32 s13, s65, 0
	s_add_i32 s75, s25, 0x8000
	s_add_i32 s76, s25, 0xa000
	v_mov_b32_e32 v131, v147
	global_load_lds_dwordx4 v[0:1], off
	v_lshl_add_u64 v[0:1], s[12:13], 0, v[132:133]
	s_mov_b32 m0, s75
	s_add_u32 s8, s8, s74
	global_load_lds_dwordx4 v[0:1], off
	v_lshl_add_u64 v[0:1], s[12:13], 0, v[130:131]
	s_mov_b32 m0, s76
	s_addc_u32 s9, s9, 0
	global_load_lds_dwordx4 v[0:1], off
	s_add_i32 m0, s25, 0x1c000
	v_lshl_add_u64 v[0:1], s[8:9], 0, v[146:147]
	global_load_lds_dwordx4 v[0:1], off
	v_lshl_add_u64 v[0:1], s[8:9], 0, v[128:129]
	s_add_i32 m0, s25, 0x1e000
	s_lshl_b32 s77, s7, 7
	global_load_lds_dwordx4 v[0:1], off
	s_waitcnt vmcnt(6)
	s_addk_i32 s77, 0x180
	s_add_i32 s78, s23, 0x80
	s_mov_b32 s79, 0
	v_add_u32_e32 v139, 0x100, v2
	s_movk_i32 s2, 0x105
	s_barrier

; #define G_STAGE(bufoff, gbase, voff) do { _Pragma("unroll") for (int _i = 0; _i < 2; ++_i) \
;         __builtin_amdgcn_global_load_lds((const unsigned*)((const char*)(gbase) + (voff)[_i]), (LAS unsigned*)(lds + (bufoff) + ldsw + _i * 8192), 16, 0, 0); } while (0)
; #define G_LDA(dst, b, h) do { _Pragma("unroll") for (int m = 0; m < 4; ++m) _Pragma("unroll") for (int k = 0; k < 2; ++k) dst[m][k] = *(const LAS bf16x8*)(lds + G_SA(b, h) + aoff + m * 2048 + k * 1024); } while (0)
; #define G_LDB(dst, b, h) do { _Pragma("unroll") for (int n = 0; n < 2; ++n) _Pragma("unroll") for (int k = 0; k < 2; ++k) dst[n][k] = *(const LAS bf16x8*)(lds + G_SB(b, h) + boff + n * 2048 + k * 1024); } while (0)
; #define G_MMA(ai, bj, At, Bt) do { __builtin_amdgcn_s_setprio(1); _Pragma("unroll") for (int m = 0; m < 4; ++m) _Pragma("unroll") for (int n = 0; n < 2; ++n) _Pragma("unroll") for (int k = 0; k < 2; ++k) \
;         acc[ai][bj][m][n] = __builtin_amdgcn_mfma_f32_16x16x32_bf16(Bt[n][k], At[m][k], acc[ai][bj][m][n], 0, 0, 0); __builtin_amdgcn_s_setprio(0); } while (0)
; #define G_WAIT_L(n) asm volatile("s_waitcnt lgkmcnt(" #n ")" ::: "memory")
; #define G_BAR __builtin_amdgcn_s_barrier()
; #define G_SCHED __builtin_amdgcn_sched_barrier(0)
; template <class J>
; DI void gemm_phase(LAS unsigned char* lds, const J& job) {
;     ...
;       const bool last = (t == nt - 2);
;       const char* a1 = cA + G_KT(t + 1);
;       const char* a2 = last ? nA + G_KT(0) : cA + G_KT(t + 2); const char* b2 = last ? nB + G_KT(0) : cB + G_KT(t + 2);
;       const char* a3 = last ? nA + G_KT(1) : cA + G_KT(t + 3); const char* b3 = last ? nB + G_KT(1) : cB + G_KT(t + 3);
;       G_LDB(B0, 0, 0); G_SCHED; G_LDA(At, 0, 0); G_STAGE(G_SA(1, 1), a1 + hstepA, voffA);
;       G_WAIT_L(8); G_BAR; G_WAIT_L(0); G_MMA(0, 0, At, B0); G_BAR; G_SCHED;
;       G_LDB(B1, 0, 1); G_STAGE(G_SB(0, 0), b2, voffB);
;       G_BAR; G_WAIT_L(0); G_MMA(0, 1, At, B1); G_BAR;
;       G_LDA(At, 0, 1); G_STAGE(G_SA(0, 0), a2, voffA);
;       G_BAR; G_WAIT_L(0); G_MMA(1, 0, At, B0); G_BAR; G_SCHED;
.LBB0_104:
	s_add_i32 s1, s56, 0xffffff80
	s_and_b32 s0, s7, 0x380
	s_and_b32 s1, s1, 0x380
	s_add_u32 s57, s64, s1
	s_addc_u32 s66, s65, 0
	s_add_u32 s1, s62, s1
	s_addc_u32 s67, s63, 0
	s_and_b32 s68, s56, 0x380
	s_add_u32 s80, s64, s68
	s_addc_u32 s69, s65, 0
	s_add_u32 s97, s62, s68
	s_addc_u32 vcc_lo, s63, 0
	s_cmp_eq_u32 s6, 4
	s_cselect_b32 s71, s83, s66
	s_cselect_b32 s70, s47, s57
	s_cselect_b32 s73, s87, s67
	s_cselect_b32 s72, s86, s1
	s_cselect_b32 s69, s94, s69
	s_cselect_b32 s68, s33, s80
	s_cselect_b32 s67, s5, vcc_lo
	s_cselect_b32 s66, s96, s97
	s_add_i32 s1, s84, 0x100
	ds_read_b128 v[140:143], v208
	ds_read_b128 v[148:151], v208 offset:1024
	ds_read_b128 v[152:155], v208 offset:2048
	ds_read_b128 v[156:159], v208 offset:3072
	s_add_u32 vcc_lo, s9, s0
	s_addc_u32 vcc_hi, s17, 0
	s_add_i32 m0, s25, 0xc000
	ds_read_b128 v[160:163], v139
	ds_read_b128 v[164:167], v139 offset:1024
	ds_read_b128 v[168:171], v139 offset:2048
	ds_read_b128 v[172:175], v139 offset:3072
	ds_read_b128 v[176:179], v139 offset:4096
	ds_read_b128 v[180:183], v139 offset:5120
	ds_read_b128 v[184:187], v139 offset:6144
	ds_read_b128 v[188:191], v139 offset:7168
	global_load_lds_dwordx4 v132, vcc
	s_add_i32 m0, s25, 0xe000
	s_nop 0
	global_load_lds_dwordx4 v130, vcc
	s_waitcnt lgkmcnt(8)
	s_barrier
	s_waitcnt lgkmcnt(0)
	v_mfma_f32_16x16x32_bf16 v[124:127], v[140:143], v[160:163], v[124:127]
	v_mfma_f32_16x16x32_bf16 v[120:123], v[152:155], v[160:163], v[120:123]
	v_mfma_f32_16x16x32_bf16 v[116:119], v[140:143], v[168:171], v[116:119]
	v_mfma_f32_16x16x32_bf16 v[108:111], v[152:155], v[168:171], v[108:111]
	v_mfma_f32_16x16x32_bf16 v[100:103], v[140:143], v[176:179], v[100:103]
	v_mfma_f32_16x16x32_bf16 v[92:95], v[152:155], v[176:179], v[92:95]
	v_mfma_f32_16x16x32_bf16 v[84:87], v[140:143], v[184:187], v[84:87]
	v_mfma_f32_16x16x32_bf16 v[76:79], v[152:155], v[184:187], v[76:79]
	v_mfma_f32_16x16x32_bf16 v[124:127], v[148:151], v[164:167], v[124:127]
	v_mfma_f32_16x16x32_bf16 v[120:123], v[156:159], v[164:167], v[120:123]
	v_mfma_f32_16x16x32_bf16 v[116:119], v[148:151], v[172:175], v[116:119]
	v_mfma_f32_16x16x32_bf16 v[108:111], v[156:159], v[172:175], v[108:111]
	v_mfma_f32_16x16x32_bf16 v[100:103], v[148:151], v[180:183], v[100:103]
	v_mfma_f32_16x16x32_bf16 v[92:95], v[156:159], v[180:183], v[92:95]
	v_mfma_f32_16x16x32_bf16 v[84:87], v[148:151], v[188:191], v[84:87]
	v_mfma_f32_16x16x32_bf16 v[76:79], v[156:159], v[188:191], v[76:79]
	s_barrier
	s_add_i32 s0, s85, 0x100
	s_add_i32 s1, s1, s24
	ds_read_b128 v[192:195], v208 offset:16384
	ds_read_b128 v[196:199], v208 offset:17408
	ds_read_b128 v[200:203], v208 offset:18432
	ds_read_b128 v[204:207], v208 offset:19456
	s_mov_b32 m0, s1
	s_nop 0
	global_load_lds_dwordx4 v146, s[72:73]
	s_add_i32 m0, s1, 0x2000
	s_nop 0
	global_load_lds_dwordx4 v128, s[72:73]
	s_barrier
	s_waitcnt lgkmcnt(0)
	v_mfma_f32_16x16x32_bf16 v[112:115], v[192:195], v[160:163], v[112:115]
	v_mfma_f32_16x16x32_bf16 v[104:107], v[200:203], v[160:163], v[104:107]
	v_mfma_f32_16x16x32_bf16 v[96:99], v[192:195], v[168:171], v[96:99]
	v_mfma_f32_16x16x32_bf16 v[88:91], v[200:203], v[168:171], v[88:91]
	v_mfma_f32_16x16x32_bf16 v[80:83], v[192:195], v[176:179], v[80:83]
	v_mfma_f32_16x16x32_bf16 v[72:75], v[200:203], v[176:179], v[72:75]
	v_mfma_f32_16x16x32_bf16 v[68:71], v[192:195], v[184:187], v[68:71]
	v_mfma_f32_16x16x32_bf16 v[64:67], v[200:203], v[184:187], v[64:67]
	v_mfma_f32_16x16x32_bf16 v[112:115], v[196:199], v[164:167], v[112:115]
	v_mfma_f32_16x16x32_bf16 v[104:107], v[204:207], v[164:167], v[104:107]
	v_mfma_f32_16x16x32_bf16 v[96:99], v[196:199], v[172:175], v[96:99]
	v_mfma_f32_16x16x32_bf16 v[88:91], v[204:207], v[172:175], v[88:91]
	v_mfma_f32_16x16x32_bf16 v[80:83], v[196:199], v[180:183], v[80:83]
	v_mfma_f32_16x16x32_bf16 v[72:75], v[204:207], v[180:183], v[72:75]
	v_mfma_f32_16x16x32_bf16 v[68:71], v[196:199], v[188:191], v[68:71]
	v_mfma_f32_16x16x32_bf16 v[64:67], v[204:207], v[188:191], v[64:67]
	s_mov_b32 m0, s25
	s_barrier
	ds_read_b128 v[160:163], v139 offset:16384
	ds_read_b128 v[164:167], v139 offset:17408
	ds_read_b128 v[168:171], v139 offset:18432
	ds_read_b128 v[172:175], v139 offset:19456
	ds_read_b128 v[176:179], v139 offset:20480
	ds_read_b128 v[180:183], v139 offset:21504
	ds_read_b128 v[184:187], v139 offset:22528
	ds_read_b128 v[188:191], v139 offset:23552
	global_load_lds_dwordx4 v132, s[70:71]
	s_mov_b32 m0, s36
	s_nop 0
	global_load_lds_dwordx4 v130, s[70:71]
	s_barrier
	s_waitcnt lgkmcnt(0)
	v_mfma_f32_16x16x32_bf16 v[60:63], v[140:143], v[160:163], v[60:63]
	v_mfma_f32_16x16x32_bf16 v[56:59], v[152:155], v[160:163], v[56:59]
	v_mfma_f32_16x16x32_bf16 v[52:55], v[140:143], v[168:171], v[52:55]
	v_mfma_f32_16x16x32_bf16 v[44:47], v[152:155], v[168:171], v[44:47]
	v_mfma_f32_16x16x32_bf16 v[36:39], v[140:143], v[176:179], v[36:39]
	v_mfma_f32_16x16x32_bf16 v[28:31], v[152:155], v[176:179], v[28:31]
	v_mfma_f32_16x16x32_bf16 v[20:23], v[140:143], v[184:187], v[20:23]
	v_mfma_f32_16x16x32_bf16 v[12:15], v[152:155], v[184:187], v[12:15]
	v_mfma_f32_16x16x32_bf16 v[60:63], v[148:151], v[164:167], v[60:63]
	v_mfma_f32_16x16x32_bf16 v[56:59], v[156:159], v[164:167], v[56:59]
	v_mfma_f32_16x16x32_bf16 v[52:55], v[148:151], v[172:175], v[52:55]
	v_mfma_f32_16x16x32_bf16 v[44:47], v[156:159], v[172:175], v[44:47]
	v_mfma_f32_16x16x32_bf16 v[36:39], v[148:151], v[180:183], v[36:39]
	v_mfma_f32_16x16x32_bf16 v[28:31], v[156:159], v[180:183], v[28:31]
	v_mfma_f32_16x16x32_bf16 v[20:23], v[148:151], v[188:191], v[20:23]
	v_mfma_f32_16x16x32_bf16 v[12:15], v[156:159], v[188:191], v[12:15]
	s_barrier
; #define G_STAGE(bufoff, gbase, voff) do { _Pragma("unroll") for (int _i = 0; _i < 2; ++_i) \
;         __builtin_amdgcn_global_load_lds((const unsigned*)((const char*)(gbase) + (voff)[_i]), (LAS unsigned*)(lds + (bufoff) + ldsw + _i * 8192), 16, 0, 0); } while (0)
; #define G_LDA(dst, b, h) do { _Pragma("unroll") for (int m = 0; m < 4; ++m) _Pragma("unroll") for (int k = 0; k < 2; ++k) dst[m][k] = *(const LAS bf16x8*)(lds + G_SA(b, h) + aoff + m * 2048 + k * 1024); } while (0)
; #define G_LDB(dst, b, h) do { _Pragma("unroll") for (int n = 0; n < 2; ++n) _Pragma("unroll") for (int k = 0; k < 2; ++k) dst[n][k] = *(const LAS bf16x8*)(lds + G_SB(b, h) + boff + n * 2048 + k * 1024); } while (0)
; #define G_MMA(ai, bj, At, Bt) do { __builtin_amdgcn_s_setprio(1); _Pragma("unroll") for (int m = 0; m < 4; ++m) _Pragma("unroll") for (int n = 0; n < 2; ++n) _Pragma("unroll") for (int k = 0; k < 2; ++k) \
;         acc[ai][bj][m][n] = __builtin_amdgcn_mfma_f32_16x16x32_bf16(Bt[n][k], At[m][k], acc[ai][bj][m][n], 0, 0, 0); __builtin_amdgcn_s_setprio(0); } while (0)
; #define G_WAIT_V(n) asm volatile("s_waitcnt vmcnt(" #n ")" ::: "memory")
; #define G_WAIT_L(n) asm volatile("s_waitcnt lgkmcnt(" #n ")" ::: "memory")
; #define G_BAR __builtin_amdgcn_s_barrier()
; #define G_SCHED __builtin_amdgcn_sched_barrier(0)
; template <class J>
; DI void gemm_phase(LAS unsigned char* lds, const J& job) {
;     ...
;       G_STAGE(G_SB(0, 1), b2 + hstepB, voffB);
;       G_WAIT_V(6); G_BAR; G_MMA(1, 1, At, B1); G_BAR;
;       G_LDB(B0, 1, 0); G_SCHED; G_LDA(At, 1, 0); G_STAGE(G_SA(0, 1), a2 + hstepA, voffA);
;       G_WAIT_L(8); G_BAR; G_WAIT_L(0); G_MMA(0, 0, At, B0); G_BAR; G_SCHED;
;       G_LDB(B1, 1, 1); G_STAGE(G_SB(1, 0), b3, voffB);
;       G_BAR; G_WAIT_L(0); G_MMA(0, 1, At, B1); G_BAR;
;       G_LDA(At, 1, 1); G_STAGE(G_SA(1, 0), a3, voffA);
	s_add_u32 s72, s72, 0x20000
	s_addc_u32 s73, s73, 0
	s_add_i32 s0, s0, s24
	s_mov_b32 m0, s0
	s_nop 0
	global_load_lds_dwordx4 v146, s[72:73]
	s_add_i32 m0, s0, 0x2000
	s_nop 0
	global_load_lds_dwordx4 v128, s[72:73]
	s_waitcnt vmcnt(6)
	s_barrier
	v_mfma_f32_16x16x32_bf16 v[48:51], v[192:195], v[160:163], v[48:51]
	v_mfma_f32_16x16x32_bf16 v[40:43], v[200:203], v[160:163], v[40:43]
	v_mfma_f32_16x16x32_bf16 v[32:35], v[192:195], v[168:171], v[32:35]
	v_mfma_f32_16x16x32_bf16 v[24:27], v[200:203], v[168:171], v[24:27]
	v_mfma_f32_16x16x32_bf16 v[16:19], v[192:195], v[176:179], v[16:19]
	v_mfma_f32_16x16x32_bf16 v[8:11], v[200:203], v[176:179], v[8:11]
	v_mfma_f32_16x16x32_bf16 v[4:7], v[192:195], v[184:187], v[4:7]
	v_mfma_f32_16x16x32_bf16 v[0:3], v[200:203], v[184:187], v[0:3]
	v_mfma_f32_16x16x32_bf16 v[48:51], v[196:199], v[164:167], v[48:51]
	v_mfma_f32_16x16x32_bf16 v[40:43], v[204:207], v[164:167], v[40:43]
	v_mfma_f32_16x16x32_bf16 v[32:35], v[196:199], v[172:175], v[32:35]
	v_mfma_f32_16x16x32_bf16 v[24:27], v[204:207], v[172:175], v[24:27]
	v_mfma_f32_16x16x32_bf16 v[16:19], v[196:199], v[180:183], v[16:19]
	v_mfma_f32_16x16x32_bf16 v[8:11], v[204:207], v[180:183], v[8:11]
	v_mfma_f32_16x16x32_bf16 v[4:7], v[196:199], v[188:191], v[4:7]
	v_mfma_f32_16x16x32_bf16 v[0:3], v[204:207], v[188:191], v[0:3]
	s_add_i32 s0, s88, 0x100
	s_barrier
	ds_read_b128 v[140:143], v208 offset:32768
	ds_read_b128 v[148:151], v208 offset:33792
	ds_read_b128 v[152:155], v208 offset:34816
	ds_read_b128 v[156:159], v208 offset:35840
	s_add_u32 s70, s70, 0x80000
	s_addc_u32 s71, s71, 0
	s_mov_b32 m0, s37
	ds_read_b128 v[160:163], v139 offset:32768
	ds_read_b128 v[164:167], v139 offset:33792
	ds_read_b128 v[168:171], v139 offset:34816
	ds_read_b128 v[172:175], v139 offset:35840
	ds_read_b128 v[176:179], v139 offset:36864
	ds_read_b128 v[180:183], v139 offset:37888
	ds_read_b128 v[184:187], v139 offset:38912
	ds_read_b128 v[188:191], v139 offset:39936
	global_load_lds_dwordx4 v132, s[70:71]
	s_mov_b32 m0, s38
	s_nop 0
	global_load_lds_dwordx4 v130, s[70:71]
	s_waitcnt lgkmcnt(8)
	s_barrier
	s_waitcnt lgkmcnt(0)
	v_mfma_f32_16x16x32_bf16 v[124:127], v[140:143], v[160:163], v[124:127]
	v_mfma_f32_16x16x32_bf16 v[120:123], v[152:155], v[160:163], v[120:123]
	v_mfma_f32_16x16x32_bf16 v[116:119], v[140:143], v[168:171], v[116:119]
	v_mfma_f32_16x16x32_bf16 v[108:111], v[152:155], v[168:171], v[108:111]
	v_mfma_f32_16x16x32_bf16 v[100:103], v[140:143], v[176:179], v[100:103]
	v_mfma_f32_16x16x32_bf16 v[92:95], v[152:155], v[176:179], v[92:95]
	v_mfma_f32_16x16x32_bf16 v[84:87], v[140:143], v[184:187], v[84:87]
	v_mfma_f32_16x16x32_bf16 v[76:79], v[152:155], v[184:187], v[76:79]
	v_mfma_f32_16x16x32_bf16 v[124:127], v[148:151], v[164:167], v[124:127]
	v_mfma_f32_16x16x32_bf16 v[120:123], v[156:159], v[164:167], v[120:123]
	v_mfma_f32_16x16x32_bf16 v[116:119], v[148:151], v[172:175], v[116:119]
	v_mfma_f32_16x16x32_bf16 v[108:111], v[156:159], v[172:175], v[108:111]
	v_mfma_f32_16x16x32_bf16 v[100:103], v[148:151], v[180:183], v[100:103]
	v_mfma_f32_16x16x32_bf16 v[92:95], v[156:159], v[180:183], v[92:95]
	v_mfma_f32_16x16x32_bf16 v[84:87], v[148:151], v[188:191], v[84:87]
	v_mfma_f32_16x16x32_bf16 v[76:79], v[156:159], v[188:191], v[76:79]
	s_barrier
	s_add_i32 s1, s89, 0x100
	s_add_i32 s0, s0, s24
	ds_read_b128 v[192:195], v208 offset:49152
	ds_read_b128 v[196:199], v208 offset:50176
	ds_read_b128 v[200:203], v208 offset:51200
	ds_read_b128 v[204:207], v208 offset:52224
	s_mov_b32 m0, s0
	s_nop 0
	global_load_lds_dwordx4 v146, s[66:67]
	s_add_i32 m0, s0, 0x2000
	s_nop 0
	global_load_lds_dwordx4 v128, s[66:67]
	s_barrier
	s_waitcnt lgkmcnt(0)
	v_mfma_f32_16x16x32_bf16 v[112:115], v[192:195], v[160:163], v[112:115]
	v_mfma_f32_16x16x32_bf16 v[104:107], v[200:203], v[160:163], v[104:107]
	v_mfma_f32_16x16x32_bf16 v[96:99], v[192:195], v[168:171], v[96:99]
	v_mfma_f32_16x16x32_bf16 v[88:91], v[200:203], v[168:171], v[88:91]
	v_mfma_f32_16x16x32_bf16 v[80:83], v[192:195], v[176:179], v[80:83]
	v_mfma_f32_16x16x32_bf16 v[72:75], v[200:203], v[176:179], v[72:75]
	v_mfma_f32_16x16x32_bf16 v[68:71], v[192:195], v[184:187], v[68:71]
	v_mfma_f32_16x16x32_bf16 v[64:67], v[200:203], v[184:187], v[64:67]
	v_mfma_f32_16x16x32_bf16 v[112:115], v[196:199], v[164:167], v[112:115]
	v_mfma_f32_16x16x32_bf16 v[104:107], v[204:207], v[164:167], v[104:107]
	v_mfma_f32_16x16x32_bf16 v[96:99], v[196:199], v[172:175], v[96:99]
	v_mfma_f32_16x16x32_bf16 v[88:91], v[204:207], v[172:175], v[88:91]
	v_mfma_f32_16x16x32_bf16 v[80:83], v[196:199], v[180:183], v[80:83]
	v_mfma_f32_16x16x32_bf16 v[72:75], v[204:207], v[180:183], v[72:75]
	v_mfma_f32_16x16x32_bf16 v[68:71], v[196:199], v[188:191], v[68:71]
	v_mfma_f32_16x16x32_bf16 v[64:67], v[204:207], v[188:191], v[64:67]
	s_mov_b32 m0, s75
	s_barrier
	ds_read_b128 v[160:163], v139 offset:49152
	ds_read_b128 v[164:167], v139 offset:50176
	ds_read_b128 v[168:171], v139 offset:51200
	ds_read_b128 v[172:175], v139 offset:52224
	ds_read_b128 v[176:179], v139 offset:53248
	ds_read_b128 v[180:183], v139 offset:54272
	ds_read_b128 v[184:187], v139 offset:55296
	ds_read_b128 v[188:191], v139 offset:56320
	global_load_lds_dwordx4 v132, s[68:69]
	s_mov_b32 m0, s76
	s_nop 0
	global_load_lds_dwordx4 v130, s[68:69]
	s_barrier
; #define G_STAGE(bufoff, gbase, voff) do { _Pragma("unroll") for (int _i = 0; _i < 2; ++_i) \
;         __builtin_amdgcn_global_load_lds((const unsigned*)((const char*)(gbase) + (voff)[_i]), (LAS unsigned*)(lds + (bufoff) + ldsw + _i * 8192), 16, 0, 0); } while (0)
; #define G_MMA(ai, bj, At, Bt) do { __builtin_amdgcn_s_setprio(1); _Pragma("unroll") for (int m = 0; m < 4; ++m) _Pragma("unroll") for (int n = 0; n < 2; ++n) _Pragma("unroll") for (int k = 0; k < 2; ++k) \
;         acc[ai][bj][m][n] = __builtin_amdgcn_mfma_f32_16x16x32_bf16(Bt[n][k], At[m][k], acc[ai][bj][m][n], 0, 0, 0); __builtin_amdgcn_s_setprio(0); } while (0)
; #define G_WAIT_V(n) asm volatile("s_waitcnt vmcnt(" #n ")" ::: "memory")
; #define G_WAIT_L(n) asm volatile("s_waitcnt lgkmcnt(" #n ")" ::: "memory")
; #define G_BAR __builtin_amdgcn_s_barrier()
; #define G_SCHED __builtin_amdgcn_sched_barrier(0)
; template <class J>
; DI void gemm_phase(LAS unsigned char* lds, const J& job) {
;     ...
;       G_BAR; G_WAIT_L(0); G_MMA(1, 0, At, B0); G_BAR; G_SCHED;
;       G_STAGE(G_SB(1, 1), b3 + hstepB, voffB);
;       G_WAIT_V(6); G_BAR; G_MMA(1, 1, At, B1); G_BAR;
	s_waitcnt lgkmcnt(0)
	v_mfma_f32_16x16x32_bf16 v[60:63], v[140:143], v[160:163], v[60:63]
	v_mfma_f32_16x16x32_bf16 v[56:59], v[152:155], v[160:163], v[56:59]
	v_mfma_f32_16x16x32_bf16 v[52:55], v[140:143], v[168:171], v[52:55]
	v_mfma_f32_16x16x32_bf16 v[44:47], v[152:155], v[168:171], v[44:47]
	v_mfma_f32_16x16x32_bf16 v[36:39], v[140:143], v[176:179], v[36:39]
	v_mfma_f32_16x16x32_bf16 v[28:31], v[152:155], v[176:179], v[28:31]
	v_mfma_f32_16x16x32_bf16 v[20:23], v[140:143], v[184:187], v[20:23]
	v_mfma_f32_16x16x32_bf16 v[12:15], v[152:155], v[184:187], v[12:15]
	v_mfma_f32_16x16x32_bf16 v[60:63], v[148:151], v[164:167], v[60:63]
	v_mfma_f32_16x16x32_bf16 v[56:59], v[156:159], v[164:167], v[56:59]
	v_mfma_f32_16x16x32_bf16 v[52:55], v[148:151], v[172:175], v[52:55]
	v_mfma_f32_16x16x32_bf16 v[44:47], v[156:159], v[172:175], v[44:47]
	v_mfma_f32_16x16x32_bf16 v[36:39], v[148:151], v[180:183], v[36:39]
	v_mfma_f32_16x16x32_bf16 v[28:31], v[156:159], v[180:183], v[28:31]
	v_mfma_f32_16x16x32_bf16 v[20:23], v[148:151], v[188:191], v[20:23]
	v_mfma_f32_16x16x32_bf16 v[12:15], v[156:159], v[188:191], v[12:15]
	s_barrier
	s_add_u32 s66, s66, 0x20000
	s_addc_u32 s67, s67, 0
	s_add_i32 s0, s1, s24
	s_mov_b32 m0, s0
	s_nop 0
	global_load_lds_dwordx4 v146, s[66:67]
	s_add_i32 m0, s0, 0x2000
	s_nop 0
	global_load_lds_dwordx4 v128, s[66:67]
	s_waitcnt vmcnt(6)
	s_barrier
	v_mfma_f32_16x16x32_bf16 v[48:51], v[192:195], v[160:163], v[48:51]
	v_mfma_f32_16x16x32_bf16 v[40:43], v[200:203], v[160:163], v[40:43]
	v_mfma_f32_16x16x32_bf16 v[32:35], v[192:195], v[168:171], v[32:35]
	v_mfma_f32_16x16x32_bf16 v[24:27], v[200:203], v[168:171], v[24:27]
	v_mfma_f32_16x16x32_bf16 v[16:19], v[192:195], v[176:179], v[16:19]
	v_mfma_f32_16x16x32_bf16 v[8:11], v[200:203], v[176:179], v[8:11]
	v_mfma_f32_16x16x32_bf16 v[4:7], v[192:195], v[184:187], v[4:7]
	v_mfma_f32_16x16x32_bf16 v[0:3], v[200:203], v[184:187], v[0:3]
	v_mfma_f32_16x16x32_bf16 v[48:51], v[196:199], v[164:167], v[48:51]
	v_mfma_f32_16x16x32_bf16 v[40:43], v[204:207], v[164:167], v[40:43]
	v_mfma_f32_16x16x32_bf16 v[32:35], v[196:199], v[172:175], v[32:35]
	v_mfma_f32_16x16x32_bf16 v[24:27], v[204:207], v[172:175], v[24:27]
	v_mfma_f32_16x16x32_bf16 v[16:19], v[196:199], v[180:183], v[16:19]
	v_mfma_f32_16x16x32_bf16 v[8:11], v[204:207], v[180:183], v[8:11]
	v_mfma_f32_16x16x32_bf16 v[4:7], v[196:199], v[188:191], v[4:7]
	v_mfma_f32_16x16x32_bf16 v[0:3], v[204:207], v[188:191], v[0:3]
	s_add_i32 s6, s6, 2
	s_addk_i32 s56, 0x100
	s_addk_i32 s7, 0x100
	s_cmp_gt_u32 s6, 5
	s_barrier
	s_cbranch_scc0 .LBB0_104
; DI unsigned pk2(float lo, float hi) { unsigned r; asm("v_cvt_pk_bf16_f32 %0, %1, %2" : "=v"(r) : "v"(lo), "v"(hi)); return r; }
; #define G_WAIT_V(n) asm volatile("s_waitcnt vmcnt(" #n ")" ::: "memory")
; #define G_BAR __builtin_amdgcn_s_barrier()
; template <class J>
; DI void gemm_phase(LAS unsigned char* lds, const J& job) {
;     ...
;     if (!has_next) break;
; #pragma unroll
;     for (int a = 0; a < 2; ++a)
; #pragma unroll
;       for (int b = 0; b < 2; ++b)
; #pragma unroll
;         for (int m = 0; m < 4; ++m)
; #pragma unroll
;           for (int n = 0; n < 2; ++n) acc[a][b][m][n] = (f32x4){0.f, 0.f, 0.f, 0.f};
;     cur = nxt; cA = nA; cB = nB; ++ui;
;   }
;   G_WAIT_V(0);
;   if (wr == 0) G_BAR;
;   G_BAR;
;   DI void epi(const Acc& acc, const Unit& u, int wr, int wc, int fr, int fq) const {
; #pragma unroll
;     for (int ai = 0; ai < 2; ++ai)
; #pragma unroll
;       for (int m = 0; m < 4; ++m) {
;         const int row = u.pm * 256 + ai * HALF + wr * 64 + m * 16 + fr;
; #pragma unroll
;         for (int bj = 0; bj < 2; ++bj) {
;           const int col = u.pn * 256 + bj * HALF + wc * 32 + 8 * fq;
;           const f32x4 v0 = acc[ai][bj][m][0], v1 = acc[ai][bj][m][1];
;           u32x4 o; o.x = pk2(v0.x, v0.y); o.y = pk2(v0.z, v0.w); o.z = pk2(v1.x, v1.y); o.w = pk2(v1.z, v1.w);
;           *(u32x4*)(Z + (size_t)row * NGATE + col) = o;
;         }
;       }
;   }
	v_mov_b32_e32 v135, v137
	v_mov_b32_e32 v134, v136
	s_lshl_b32 s0, s22, 8
	s_add_i32 s0, s0, s44
	v_add_u32_e32 v134, s0, v134
	s_lshl_b32 s0, s46, 8
	s_or_b32 s0, s0, s45
	v_cvt_pk_bf16_f32 v68, v68, v69
	v_cvt_pk_bf16_f32 v69, v70, v71
	v_cvt_pk_bf16_f32 v70, v64, v65
	v_add_u32_e32 v64, 0x80, v134
	v_lshl_add_u32 v140, v135, 3, s0
	v_ashrrev_i32_e32 v135, 31, v134
	v_ashrrev_i32_e32 v65, 31, v64
	v_lshlrev_b64 v[142:143], 14, v[134:135]
	v_ashrrev_i32_e32 v141, 31, v140
	v_lshlrev_b64 v[64:65], 14, v[64:65]
	v_cvt_pk_bf16_f32 v124, v124, v125
	v_cvt_pk_bf16_f32 v125, v126, v127
	v_cvt_pk_bf16_f32 v126, v120, v121
	v_cvt_pk_bf16_f32 v127, v122, v123
	v_lshl_add_u64 v[122:123], s[26:27], 0, v[142:143]
	v_lshlrev_b64 v[120:121], 1, v[140:141]
	v_cvt_pk_bf16_f32 v112, v112, v113
	v_cvt_pk_bf16_f32 v113, v114, v115
	v_cvt_pk_bf16_f32 v114, v104, v105
	v_add_u32_e32 v104, 16, v134
	v_cvt_pk_bf16_f32 v60, v60, v61
	v_cvt_pk_bf16_f32 v61, v62, v63
	v_cvt_pk_bf16_f32 v62, v56, v57
	v_lshl_add_u64 v[56:57], s[26:27], 0, v[64:65]
	v_cvt_pk_bf16_f32 v48, v48, v49
	v_cvt_pk_bf16_f32 v49, v50, v51
	v_cvt_pk_bf16_f32 v50, v40, v41
	v_add_u32_e32 v40, 0x90, v134
	v_lshl_add_u64 v[122:123], v[122:123], 0, v[120:121]
	v_ashrrev_i32_e32 v105, 31, v104
	v_lshl_add_u64 v[56:57], v[56:57], 0, v[120:121]
	v_ashrrev_i32_e32 v41, 31, v40
	v_cvt_pk_bf16_f32 v115, v106, v107
	global_store_dwordx4 v[122:123], v[112:115], off offset:256
	v_cvt_pk_bf16_f32 v51, v42, v43
	global_store_dwordx4 v[56:57], v[48:51], off offset:256
	v_cvt_pk_bf16_f32 v106, v108, v109
	v_cvt_pk_bf16_f32 v96, v96, v97
	v_cvt_pk_bf16_f32 v97, v98, v99
	s_nop 0
	v_lshlrev_b64 v[112:113], 14, v[104:105]
	v_lshl_add_u64 v[108:109], s[26:27], 0, v[112:113]
	v_lshlrev_b64 v[48:49], 14, v[40:41]
	v_cvt_pk_bf16_f32 v98, v88, v89
	v_add_u32_e32 v88, 32, v134
	v_cvt_pk_bf16_f32 v42, v44, v45
	v_lshl_add_u64 v[44:45], s[26:27], 0, v[48:49]
	v_cvt_pk_bf16_f32 v32, v32, v33
	v_cvt_pk_bf16_f32 v33, v34, v35
	v_cvt_pk_bf16_f32 v34, v24, v25
	v_add_u32_e32 v24, 0xa0, v134
	v_lshl_add_u64 v[108:109], v[108:109], 0, v[120:121]
	v_ashrrev_i32_e32 v89, 31, v88
	v_lshl_add_u64 v[44:45], v[44:45], 0, v[120:121]
	v_ashrrev_i32_e32 v25, 31, v24
	v_cvt_pk_bf16_f32 v99, v90, v91
	global_store_dwordx4 v[108:109], v[96:99], off offset:256
	v_cvt_pk_bf16_f32 v35, v26, v27
	global_store_dwordx4 v[44:45], v[32:35], off offset:256
	v_cvt_pk_bf16_f32 v90, v92, v93
	v_cvt_pk_bf16_f32 v80, v80, v81
	v_cvt_pk_bf16_f32 v81, v82, v83
	s_nop 0
	v_lshlrev_b64 v[96:97], 14, v[88:89]
	v_lshl_add_u64 v[92:93], s[26:27], 0, v[96:97]
	v_lshlrev_b64 v[32:33], 14, v[24:25]
	v_cvt_pk_bf16_f32 v82, v72, v73
	v_add_u32_e32 v72, 48, v134
	v_cvt_pk_bf16_f32 v26, v28, v29
	v_lshl_add_u64 v[28:29], s[26:27], 0, v[32:33]
	v_cvt_pk_bf16_f32 v16, v16, v17
	v_cvt_pk_bf16_f32 v17, v18, v19
	v_cvt_pk_bf16_f32 v18, v8, v9
	v_add_u32_e32 v8, 0xb0, v134
	v_lshl_add_u64 v[92:93], v[92:93], 0, v[120:121]
	v_ashrrev_i32_e32 v73, 31, v72
	v_lshl_add_u64 v[28:29], v[28:29], 0, v[120:121]
	v_ashrrev_i32_e32 v9, 31, v8
	v_cvt_pk_bf16_f32 v83, v74, v75
	global_store_dwordx4 v[92:93], v[80:83], off offset:256
	v_cvt_pk_bf16_f32 v19, v10, v11
	global_store_dwordx4 v[28:29], v[16:19], off offset:256
	v_cvt_pk_bf16_f32 v74, v76, v77
	v_cvt_pk_bf16_f32 v10, v12, v13
	s_and_b64 vcc, exec, s[12:13]
	v_lshlrev_b64 v[80:81], 14, v[72:73]
	v_lshlrev_b64 v[16:17], 14, v[8:9]
	v_lshl_add_u64 v[76:77], s[26:27], 0, v[80:81]
	v_lshl_add_u64 v[12:13], s[26:27], 0, v[16:17]
	v_lshl_add_u64 v[76:77], v[76:77], 0, v[120:121]
	v_lshl_add_u64 v[12:13], v[12:13], 0, v[120:121]
	s_mov_b32 s46, s8
	s_mov_b32 s22, s16
	s_mov_b64 s[62:63], s[20:21]
	s_mov_b64 s[64:65], s[18:19]
	global_store_dwordx4 v[122:123], v[124:127], off
	v_cvt_pk_bf16_f32 v104, v116, v117
	v_cvt_pk_bf16_f32 v105, v118, v119
	v_cvt_pk_bf16_f32 v107, v110, v111
	global_store_dwordx4 v[108:109], v[104:107], off
	v_cvt_pk_bf16_f32 v88, v100, v101
	v_cvt_pk_bf16_f32 v89, v102, v103
	v_cvt_pk_bf16_f32 v91, v94, v95
	global_store_dwordx4 v[92:93], v[88:91], off
	v_cvt_pk_bf16_f32 v72, v84, v85
	v_cvt_pk_bf16_f32 v73, v86, v87
	v_cvt_pk_bf16_f32 v75, v78, v79
	global_store_dwordx4 v[76:77], v[72:75], off
	v_cvt_pk_bf16_f32 v71, v66, v67
	global_store_dwordx4 v[76:77], v[68:71], off offset:256
	v_cvt_pk_bf16_f32 v63, v58, v59
	global_store_dwordx4 v[56:57], v[60:63], off
	v_cvt_pk_bf16_f32 v40, v52, v53
	v_cvt_pk_bf16_f32 v41, v54, v55
	v_cvt_pk_bf16_f32 v43, v46, v47
	global_store_dwordx4 v[44:45], v[40:43], off
	v_cvt_pk_bf16_f32 v24, v36, v37
	v_cvt_pk_bf16_f32 v25, v38, v39
	v_cvt_pk_bf16_f32 v27, v30, v31
	global_store_dwordx4 v[28:29], v[24:27], off
	v_cvt_pk_bf16_f32 v8, v20, v21
	v_cvt_pk_bf16_f32 v9, v22, v23
	v_cvt_pk_bf16_f32 v11, v14, v15
	global_store_dwordx4 v[12:13], v[8:11], off
	v_cvt_pk_bf16_f32 v4, v4, v5
	v_cvt_pk_bf16_f32 v5, v6, v7
	v_cvt_pk_bf16_f32 v6, v0, v1
	v_cvt_pk_bf16_f32 v7, v2, v3
	global_store_dwordx4 v[12:13], v[4:7], off offset:256
	s_cbranch_vccz .LBB0_101
	s_setprio 0
	s_waitcnt vmcnt(0)
	v_readlane_b32 s44, v255, 6
	s_cmpk_gt_u32 s4, 0xff
	v_readlane_b32 s45, v255, 7
	s_cbranch_scc1 .LBB0_108
	s_barrier

; DI int my_tid() { int t = threadIdx.x; asm volatile("" : "+v"(t)); return t; }
; #define G_STAGE(bufoff, gbase, voff) do { _Pragma("unroll") for (int _i = 0; _i < 2; ++_i) \
;         __builtin_amdgcn_global_load_lds((const unsigned*)((const char*)(gbase) + (voff)[_i]), (LAS unsigned*)(lds + (bufoff) + ldsw + _i * 8192), 16, 0, 0); } while (0)
; #define G_WAIT_V(n) asm volatile("s_waitcnt vmcnt(" #n ")" ::: "memory")
; #define G_BAR __builtin_amdgcn_s_barrier()
;   DI int brow_of(int R) const { return (R & ~31) + perm32(R & 31); }
;   DI const char* aptr(const Unit& u) const { return (const char*)(h + (size_t)u.pm * 256 * DM); }
;   DI const char* bptr(const Unit& u) const { return (const char*)(winT + (size_t)u.pn * 256 * DM); }
;   DI int brow_of(int R) const { return (R & ~31) + perm32(R & 31); }
;   DI bool next(int i, Unit& u) const { const int L = i * G + c; if (L >= nunits) return false; u.kind = 0; decode_unit(L, 65, 32, u.pm, u.pn); return true; }
; template <class J>
; DI void gemm_phase(LAS unsigned char* lds, const J& job) {
;   const int tid = my_tid(), wid = __builtin_amdgcn_readfirstlane(tid >> 6), lane = tid & 63, wr = wid >> 2, wc = wid & 3, fr = lane & 15, fq = lane >> 4;
;   const int nt = job.nt;
;   unsigned voffA[2], voffB[2];
; #pragma unroll
;   for (int i = 0; i < 2; ++i) { int R, C; stage_rc(tid * 16 + i * 8192, R, C); const int Rb = job.brow_of(R);
;     voffA[i] = (unsigned)(R * job.lda + C) * 2u; voffB[i] = (unsigned)(Rb * job.ldb + C) * 2u; }
;   const size_t kstep = (size_t)(BK * 2);
;   const size_t hstepA = (size_t)HALF * job.lda * 2, hstepB = (size_t)job.bhalf_rows() * job.ldb * 2;
;   const unsigned ldsw = (unsigned)wid * 1024u;
;   const int aoff = lds_byte(wr * 64 + fr, fq * 8), boff = lds_byte(wc * 32 + fr, fq * 8);
;     ...
;   G_STAGE(G_SB(0, 0), cB + G_KT(0), voffB); G_STAGE(G_SA(0, 0), cA + G_KT(0), voffA); G_STAGE(G_SB(0, 1), cB + hstepB + G_KT(0), voffB); G_STAGE(G_SA(0, 1), cA + hstepA + G_KT(0), voffA);
;   if (wr == 1) G_BAR;
;   G_WAIT_V(4); G_BAR;
;   G_STAGE(G_SB(1, 0), cB + G_KT(1), voffB); G_STAGE(G_SA(1, 0), cA + G_KT(1), voffA); G_STAGE(G_SB(1, 1), cB + hstepB + G_KT(1), voffB);
;   G_WAIT_V(6); G_BAR;
;   for (;;) {
;     const bool has_next = job.next(ui + 1, nxt);
;     const char* nA = has_next ? job.aptr(nxt) : cA; const char* nB = has_next ? job.bptr(nxt) : cB;
.LBB0_277:
	s_lshl_b32 s1, s16, 5
	s_and_b32 s38, s1, 0x60
	s_lshl_b32 s37, s6, 6
	s_lshl_b32 s0, s6, 13
	s_lshl_b32 s1, s38, 7
	s_or_b32 s44, s14, 0x80
	s_add_u32 s18, s66, s44
	s_addc_u32 s19, s67, 0
	s_add_i32 m0, s15, 0x18000
	v_lshl_add_u64 v[2:3], s[18:19], 0, v[146:147]
	v_mov_b32_e32 v133, v147
	s_waitcnt vmcnt(4)
	s_barrier
	global_load_lds_dwordx4 v[2:3], off
	s_add_i32 m0, s15, 0x1a000
	v_lshl_add_u64 v[2:3], s[18:19], 0, v[132:133]
	s_add_u32 s18, s68, s44
	v_mov_b32_e32 v129, v147
	s_addc_u32 s19, s69, 0
	s_add_i32 s45, s15, 0x8000
	s_add_i32 s65, s15, 0xa000
	v_mov_b32_e32 v131, v147
	global_load_lds_dwordx4 v[2:3], off
	v_lshl_add_u64 v[2:3], s[18:19], 0, v[128:129]
	s_mov_b32 m0, s45
	s_add_u32 s16, s9, s44
	global_load_lds_dwordx4 v[2:3], off
	v_lshl_add_u64 v[2:3], s[18:19], 0, v[130:131]
	s_mov_b32 m0, s65
	s_addc_u32 s17, s17, 0
	global_load_lds_dwordx4 v[2:3], off
	s_add_i32 m0, s15, 0x1c000
	v_lshl_add_u64 v[2:3], s[16:17], 0, v[146:147]
	global_load_lds_dwordx4 v[2:3], off
	v_lshl_add_u64 v[2:3], s[16:17], 0, v[132:133]
	s_add_i32 m0, s15, 0x1e000
	v_bfe_u32 v149, v0, 4, 2
	global_load_lds_dwordx4 v[2:3], off
	v_and_b32_e32 v148, 15, v0
	v_lshlrev_b32_e32 v1, 4, v149
	v_lshlrev_b32_e32 v0, 2, v0
	v_lshl_or_b32 v1, v148, 6, v1
	v_and_b32_e32 v0, 32, v0
	v_bitop3_b32 v2, v1, s0, v0 bitop3:0xde
	v_bitop3_b32 v150, v1, s1, v0 bitop3:0xde
	v_add_u32_e32 v208, 0x10100, v150
	v_readlane_b32 s0, v255, 14
	s_and_b32 s78, s43, 7
	v_readlane_b32 s1, v255, 15
	s_and_b64 s[16:17], s[0:1], exec
	s_cselect_b32 s0, 0x2000000, 0
	s_waitcnt lgkmcnt(0)
	s_add_u32 s83, s10, s0
	s_addc_u32 s86, s11, 0
	s_lshl_b32 s0, s7, 9
	s_waitcnt vmcnt(6)
	s_or_b32 s87, s0, 0x180
	s_and_b32 s0, s7, 7
	s_lshl_b32 s94, s0, 9
	s_mov_b32 s79, 0
	s_bitset1_b32 s94, 7
	v_add_u32_e32 v151, 0x100, v2
	s_movk_i32 s2, 0xc1
	s_barrier
	s_branch .LBB0_279

; #define G_STAGE(bufoff, gbase, voff) do { _Pragma("unroll") for (int _i = 0; _i < 2; ++_i) \
;         __builtin_amdgcn_global_load_lds((const unsigned*)((const char*)(gbase) + (voff)[_i]), (LAS unsigned*)(lds + (bufoff) + ldsw + _i * 8192), 16, 0, 0); } while (0)
; #define G_LDA(dst, b, h) do { _Pragma("unroll") for (int m = 0; m < 4; ++m) _Pragma("unroll") for (int k = 0; k < 2; ++k) dst[m][k] = *(const LAS bf16x8*)(lds + G_SA(b, h) + aoff + m * 2048 + k * 1024); } while (0)
; #define G_LDB(dst, b, h) do { _Pragma("unroll") for (int n = 0; n < 2; ++n) _Pragma("unroll") for (int k = 0; k < 2; ++k) dst[n][k] = *(const LAS bf16x8*)(lds + G_SB(b, h) + boff + n * 2048 + k * 1024); } while (0)
; #define G_MMA(ai, bj, At, Bt) do { __builtin_amdgcn_s_setprio(1); _Pragma("unroll") for (int m = 0; m < 4; ++m) _Pragma("unroll") for (int n = 0; n < 2; ++n) _Pragma("unroll") for (int k = 0; k < 2; ++k) \
;         acc[ai][bj][m][n] = __builtin_amdgcn_mfma_f32_16x16x32_bf16(Bt[n][k], At[m][k], acc[ai][bj][m][n], 0, 0, 0); __builtin_amdgcn_s_setprio(0); } while (0)
; #define G_WAIT_V(n) asm volatile("s_waitcnt vmcnt(" #n ")" ::: "memory")
; #define G_WAIT_L(n) asm volatile("s_waitcnt lgkmcnt(" #n ")" ::: "memory")
; #define G_BAR __builtin_amdgcn_s_barrier()
; #define G_SCHED __builtin_amdgcn_sched_barrier(0)
; template <class J>
; DI void gemm_phase(LAS unsigned char* lds, const J& job) {
;     ...
;       const char* a1 = cA + G_KT(t + 1);
;       const char* a2 = last ? nA + G_KT(0) : cA + G_KT(t + 2); const char* b2 = last ? nB + G_KT(0) : cB + G_KT(t + 2);
;       const char* a3 = last ? nA + G_KT(1) : cA + G_KT(t + 3); const char* b3 = last ? nB + G_KT(1) : cB + G_KT(t + 3);
;       G_LDB(B0, 0, 0); G_SCHED; G_LDA(At, 0, 0); G_STAGE(G_SA(1, 1), a1 + hstepA, voffA);
;       G_WAIT_L(8); G_BAR; G_WAIT_L(0); G_MMA(0, 0, At, B0); G_BAR; G_SCHED;
;       G_LDB(B1, 0, 1); G_STAGE(G_SB(0, 0), b2, voffB);
;       G_BAR; G_WAIT_L(0); G_MMA(0, 1, At, B1); G_BAR;
;       G_LDA(At, 0, 1); G_STAGE(G_SA(0, 0), a2, voffA);
;       G_BAR; G_WAIT_L(0); G_MMA(1, 0, At, B0); G_BAR; G_SCHED;
;       G_STAGE(G_SB(0, 1), b2 + hstepB, voffB);
;       G_WAIT_V(6); G_BAR; G_MMA(1, 1, At, B1); G_BAR;
.LBB0_282:
	s_add_i32 s1, s56, 0xffffff80
	s_and_b32 s0, s7, 0xf80
	s_and_b32 s1, s1, 0xf00
	s_add_u32 s10, s68, s1
	s_addc_u32 s11, s69, 0
	s_add_u32 s1, s66, s1
	s_addc_u32 s57, s67, 0
	s_and_b32 s70, s56, 0xf80
	s_add_u32 s71, s68, s70
	s_addc_u32 s72, s69, 0
	s_add_u32 s70, s66, s70
	s_addc_u32 s80, s67, 0
	s_cmp_eq_u32 s6, 28
	s_cselect_b32 s75, s46, s11
	s_cselect_b32 s74, s21, s10
	s_cselect_b32 s77, s96, s57
	s_cselect_b32 s76, s47, s1
	s_cselect_b32 s73, s97, s72
	s_cselect_b32 s72, s33, s71
	s_cselect_b32 s71, vcc_hi, s80
	s_cselect_b32 s70, vcc_lo, s70
	s_add_i32 s1, s84, 0x100
	ds_read_b128 v[134:137], v208
	ds_read_b128 v[138:141], v208 offset:1024
	ds_read_b128 v[152:155], v208 offset:2048
	ds_read_b128 v[156:159], v208 offset:3072
	s_add_u32 s10, s9, s0
	s_addc_u32 s11, s19, 0
	s_add_i32 m0, s15, 0xc000
	ds_read_b128 v[160:163], v151
	ds_read_b128 v[164:167], v151 offset:1024
	ds_read_b128 v[168:171], v151 offset:2048
	ds_read_b128 v[172:175], v151 offset:3072
	ds_read_b128 v[176:179], v151 offset:4096
	ds_read_b128 v[180:183], v151 offset:5120
	ds_read_b128 v[184:187], v151 offset:6144
	ds_read_b128 v[188:191], v151 offset:7168
	global_load_lds_dwordx4 v128, s[10:11]
	s_add_i32 m0, s15, 0xe000
	s_nop 0
	global_load_lds_dwordx4 v130, s[10:11]
	s_waitcnt lgkmcnt(8)
	s_barrier
	s_waitcnt lgkmcnt(0)
	v_mfma_f32_16x16x32_bf16 v[124:127], v[134:137], v[160:163], v[124:127]
	v_mfma_f32_16x16x32_bf16 v[120:123], v[152:155], v[160:163], v[120:123]
	v_mfma_f32_16x16x32_bf16 v[108:111], v[134:137], v[168:171], v[108:111]
	v_mfma_f32_16x16x32_bf16 v[104:107], v[152:155], v[168:171], v[104:107]
	v_mfma_f32_16x16x32_bf16 v[92:95], v[134:137], v[176:179], v[92:95]
	v_mfma_f32_16x16x32_bf16 v[88:91], v[152:155], v[176:179], v[88:91]
	v_mfma_f32_16x16x32_bf16 v[76:79], v[134:137], v[184:187], v[76:79]
	v_mfma_f32_16x16x32_bf16 v[72:75], v[152:155], v[184:187], v[72:75]
	v_mfma_f32_16x16x32_bf16 v[124:127], v[138:141], v[164:167], v[124:127]
	v_mfma_f32_16x16x32_bf16 v[120:123], v[156:159], v[164:167], v[120:123]
	v_mfma_f32_16x16x32_bf16 v[108:111], v[138:141], v[172:175], v[108:111]
	v_mfma_f32_16x16x32_bf16 v[104:107], v[156:159], v[172:175], v[104:107]
	v_mfma_f32_16x16x32_bf16 v[92:95], v[138:141], v[180:183], v[92:95]
	v_mfma_f32_16x16x32_bf16 v[88:91], v[156:159], v[180:183], v[88:91]
	v_mfma_f32_16x16x32_bf16 v[76:79], v[138:141], v[188:191], v[76:79]
	v_mfma_f32_16x16x32_bf16 v[72:75], v[156:159], v[188:191], v[72:75]
	s_barrier
	s_add_i32 s0, s85, 0x100
	s_add_i32 s1, s1, s5
	ds_read_b128 v[192:195], v208 offset:16384
	ds_read_b128 v[196:199], v208 offset:17408
	ds_read_b128 v[200:203], v208 offset:18432
	ds_read_b128 v[204:207], v208 offset:19456
	s_mov_b32 m0, s1
	s_nop 0
	global_load_lds_dwordx4 v146, s[76:77]
	s_add_i32 m0, s1, 0x2000
	s_nop 0
	global_load_lds_dwordx4 v132, s[76:77]
	s_barrier
	s_waitcnt lgkmcnt(0)
	v_mfma_f32_16x16x32_bf16 v[116:119], v[192:195], v[160:163], v[116:119]
	v_mfma_f32_16x16x32_bf16 v[112:115], v[200:203], v[160:163], v[112:115]
	v_mfma_f32_16x16x32_bf16 v[100:103], v[192:195], v[168:171], v[100:103]
	v_mfma_f32_16x16x32_bf16 v[96:99], v[200:203], v[168:171], v[96:99]
	v_mfma_f32_16x16x32_bf16 v[84:87], v[192:195], v[176:179], v[84:87]
	v_mfma_f32_16x16x32_bf16 v[80:83], v[200:203], v[176:179], v[80:83]
	v_mfma_f32_16x16x32_bf16 v[68:71], v[192:195], v[184:187], v[68:71]
	v_mfma_f32_16x16x32_bf16 v[64:67], v[200:203], v[184:187], v[64:67]
	v_mfma_f32_16x16x32_bf16 v[116:119], v[196:199], v[164:167], v[116:119]
	v_mfma_f32_16x16x32_bf16 v[112:115], v[204:207], v[164:167], v[112:115]
	v_mfma_f32_16x16x32_bf16 v[100:103], v[196:199], v[172:175], v[100:103]
	v_mfma_f32_16x16x32_bf16 v[96:99], v[204:207], v[172:175], v[96:99]
	v_mfma_f32_16x16x32_bf16 v[84:87], v[196:199], v[180:183], v[84:87]
	v_mfma_f32_16x16x32_bf16 v[80:83], v[204:207], v[180:183], v[80:83]
	v_mfma_f32_16x16x32_bf16 v[68:71], v[196:199], v[188:191], v[68:71]
	v_mfma_f32_16x16x32_bf16 v[64:67], v[204:207], v[188:191], v[64:67]
	s_mov_b32 m0, s15
	s_barrier
	ds_read_b128 v[160:163], v151 offset:16384
	ds_read_b128 v[164:167], v151 offset:17408
	ds_read_b128 v[168:171], v151 offset:18432
	ds_read_b128 v[172:175], v151 offset:19456
	ds_read_b128 v[176:179], v151 offset:20480
	ds_read_b128 v[180:183], v151 offset:21504
	ds_read_b128 v[184:187], v151 offset:22528
	ds_read_b128 v[188:191], v151 offset:23552
	global_load_lds_dwordx4 v128, s[74:75]
	s_mov_b32 m0, s24
	s_nop 0
	global_load_lds_dwordx4 v130, s[74:75]
	s_barrier
	s_waitcnt lgkmcnt(0)
	v_mfma_f32_16x16x32_bf16 v[60:63], v[134:137], v[160:163], v[60:63]
	v_mfma_f32_16x16x32_bf16 v[56:59], v[152:155], v[160:163], v[56:59]
	v_mfma_f32_16x16x32_bf16 v[44:47], v[134:137], v[168:171], v[44:47]
	v_mfma_f32_16x16x32_bf16 v[40:43], v[152:155], v[168:171], v[40:43]
	v_mfma_f32_16x16x32_bf16 v[28:31], v[134:137], v[176:179], v[28:31]
	v_mfma_f32_16x16x32_bf16 v[24:27], v[152:155], v[176:179], v[24:27]
	v_mfma_f32_16x16x32_bf16 v[12:15], v[134:137], v[184:187], v[12:15]
	v_mfma_f32_16x16x32_bf16 v[8:11], v[152:155], v[184:187], v[8:11]
	v_mfma_f32_16x16x32_bf16 v[60:63], v[138:141], v[164:167], v[60:63]
	v_mfma_f32_16x16x32_bf16 v[56:59], v[156:159], v[164:167], v[56:59]
	v_mfma_f32_16x16x32_bf16 v[44:47], v[138:141], v[172:175], v[44:47]
	v_mfma_f32_16x16x32_bf16 v[40:43], v[156:159], v[172:175], v[40:43]
	v_mfma_f32_16x16x32_bf16 v[28:31], v[138:141], v[180:183], v[28:31]
	v_mfma_f32_16x16x32_bf16 v[24:27], v[156:159], v[180:183], v[24:27]
	v_mfma_f32_16x16x32_bf16 v[12:15], v[138:141], v[188:191], v[12:15]
	v_mfma_f32_16x16x32_bf16 v[8:11], v[156:159], v[188:191], v[8:11]
	s_barrier
; #define G_STAGE(bufoff, gbase, voff) do { _Pragma("unroll") for (int _i = 0; _i < 2; ++_i) \
;         __builtin_amdgcn_global_load_lds((const unsigned*)((const char*)(gbase) + (voff)[_i]), (LAS unsigned*)(lds + (bufoff) + ldsw + _i * 8192), 16, 0, 0); } while (0)
; #define G_LDA(dst, b, h) do { _Pragma("unroll") for (int m = 0; m < 4; ++m) _Pragma("unroll") for (int k = 0; k < 2; ++k) dst[m][k] = *(const LAS bf16x8*)(lds + G_SA(b, h) + aoff + m * 2048 + k * 1024); } while (0)
; #define G_LDB(dst, b, h) do { _Pragma("unroll") for (int n = 0; n < 2; ++n) _Pragma("unroll") for (int k = 0; k < 2; ++k) dst[n][k] = *(const LAS bf16x8*)(lds + G_SB(b, h) + boff + n * 2048 + k * 1024); } while (0)
; #define G_MMA(ai, bj, At, Bt) do { __builtin_amdgcn_s_setprio(1); _Pragma("unroll") for (int m = 0; m < 4; ++m) _Pragma("unroll") for (int n = 0; n < 2; ++n) _Pragma("unroll") for (int k = 0; k < 2; ++k) \
;         acc[ai][bj][m][n] = __builtin_amdgcn_mfma_f32_16x16x32_bf16(Bt[n][k], At[m][k], acc[ai][bj][m][n], 0, 0, 0); __builtin_amdgcn_s_setprio(0); } while (0)
; #define G_WAIT_V(n) asm volatile("s_waitcnt vmcnt(" #n ")" ::: "memory")
; #define G_WAIT_L(n) asm volatile("s_waitcnt lgkmcnt(" #n ")" ::: "memory")
; #define G_BAR __builtin_amdgcn_s_barrier()
; #define G_SCHED __builtin_amdgcn_sched_barrier(0)
; template <class J>
; DI void gemm_phase(LAS unsigned char* lds, const J& job) {
;     ...
;       G_STAGE(G_SB(0, 1), b2 + hstepB, voffB);
;       G_WAIT_V(6); G_BAR; G_MMA(1, 1, At, B1); G_BAR;
;       G_LDB(B0, 1, 0); G_SCHED; G_LDA(At, 1, 0); G_STAGE(G_SA(0, 1), a2 + hstepA, voffA);
;       G_WAIT_L(8); G_BAR; G_WAIT_L(0); G_MMA(0, 0, At, B0); G_BAR; G_SCHED;
;       G_LDB(B1, 1, 1); G_STAGE(G_SB(1, 0), b3, voffB);
;       G_BAR; G_WAIT_L(0); G_MMA(0, 1, At, B1); G_BAR;
;       G_LDA(At, 1, 1); G_STAGE(G_SA(1, 0), a3, voffA);
;       G_BAR; G_WAIT_L(0); G_MMA(1, 0, At, B0); G_BAR; G_SCHED;
	s_add_u32 s10, s76, 0x80000
	s_addc_u32 s11, s77, 0
	s_add_i32 s0, s0, s5
	s_mov_b32 m0, s0
	s_nop 0
	global_load_lds_dwordx4 v146, s[10:11]
	s_add_i32 m0, s0, 0x2000
	s_nop 0
	global_load_lds_dwordx4 v132, s[10:11]
	s_waitcnt vmcnt(6)
	s_barrier
	v_mfma_f32_16x16x32_bf16 v[52:55], v[192:195], v[160:163], v[52:55]
	v_mfma_f32_16x16x32_bf16 v[48:51], v[200:203], v[160:163], v[48:51]
	v_mfma_f32_16x16x32_bf16 v[36:39], v[192:195], v[168:171], v[36:39]
	v_mfma_f32_16x16x32_bf16 v[32:35], v[200:203], v[168:171], v[32:35]
	v_mfma_f32_16x16x32_bf16 v[20:23], v[192:195], v[176:179], v[20:23]
	v_mfma_f32_16x16x32_bf16 v[16:19], v[200:203], v[176:179], v[16:19]
	v_mfma_f32_16x16x32_bf16 v[4:7], v[192:195], v[184:187], v[4:7]
	v_mfma_f32_16x16x32_bf16 v[0:3], v[200:203], v[184:187], v[0:3]
	v_mfma_f32_16x16x32_bf16 v[52:55], v[196:199], v[164:167], v[52:55]
	v_mfma_f32_16x16x32_bf16 v[48:51], v[204:207], v[164:167], v[48:51]
	v_mfma_f32_16x16x32_bf16 v[36:39], v[196:199], v[172:175], v[36:39]
	v_mfma_f32_16x16x32_bf16 v[32:35], v[204:207], v[172:175], v[32:35]
	v_mfma_f32_16x16x32_bf16 v[20:23], v[196:199], v[180:183], v[20:23]
	v_mfma_f32_16x16x32_bf16 v[16:19], v[204:207], v[180:183], v[16:19]
	v_mfma_f32_16x16x32_bf16 v[4:7], v[196:199], v[188:191], v[4:7]
	v_mfma_f32_16x16x32_bf16 v[0:3], v[204:207], v[188:191], v[0:3]
	s_add_i32 s0, s88, 0x100
	s_barrier
	ds_read_b128 v[134:137], v208 offset:32768
	ds_read_b128 v[138:141], v208 offset:33792
	ds_read_b128 v[152:155], v208 offset:34816
	ds_read_b128 v[156:159], v208 offset:35840
	s_add_u32 s10, s74, 0x80000
	s_addc_u32 s11, s75, 0
	s_mov_b32 m0, s25
	ds_read_b128 v[160:163], v151 offset:32768
	ds_read_b128 v[164:167], v151 offset:33792
	ds_read_b128 v[168:171], v151 offset:34816
	ds_read_b128 v[172:175], v151 offset:35840
	ds_read_b128 v[176:179], v151 offset:36864
	ds_read_b128 v[180:183], v151 offset:37888
	ds_read_b128 v[184:187], v151 offset:38912
	ds_read_b128 v[188:191], v151 offset:39936
	global_load_lds_dwordx4 v128, s[10:11]
	s_mov_b32 m0, s36
	s_nop 0
	global_load_lds_dwordx4 v130, s[10:11]
	s_waitcnt lgkmcnt(8)
	s_barrier
	s_waitcnt lgkmcnt(0)
	v_mfma_f32_16x16x32_bf16 v[124:127], v[134:137], v[160:163], v[124:127]
	v_mfma_f32_16x16x32_bf16 v[120:123], v[152:155], v[160:163], v[120:123]
	v_mfma_f32_16x16x32_bf16 v[108:111], v[134:137], v[168:171], v[108:111]
	v_mfma_f32_16x16x32_bf16 v[104:107], v[152:155], v[168:171], v[104:107]
	v_mfma_f32_16x16x32_bf16 v[92:95], v[134:137], v[176:179], v[92:95]
	v_mfma_f32_16x16x32_bf16 v[88:91], v[152:155], v[176:179], v[88:91]
	v_mfma_f32_16x16x32_bf16 v[76:79], v[134:137], v[184:187], v[76:79]
	v_mfma_f32_16x16x32_bf16 v[72:75], v[152:155], v[184:187], v[72:75]
	v_mfma_f32_16x16x32_bf16 v[124:127], v[138:141], v[164:167], v[124:127]
	v_mfma_f32_16x16x32_bf16 v[120:123], v[156:159], v[164:167], v[120:123]
	v_mfma_f32_16x16x32_bf16 v[108:111], v[138:141], v[172:175], v[108:111]
	v_mfma_f32_16x16x32_bf16 v[104:107], v[156:159], v[172:175], v[104:107]
	v_mfma_f32_16x16x32_bf16 v[92:95], v[138:141], v[180:183], v[92:95]
	v_mfma_f32_16x16x32_bf16 v[88:91], v[156:159], v[180:183], v[88:91]
	v_mfma_f32_16x16x32_bf16 v[76:79], v[138:141], v[188:191], v[76:79]
	v_mfma_f32_16x16x32_bf16 v[72:75], v[156:159], v[188:191], v[72:75]
	s_barrier
	s_add_i32 s1, s89, 0x100
	s_add_i32 s0, s0, s5
	ds_read_b128 v[192:195], v208 offset:49152
	ds_read_b128 v[196:199], v208 offset:50176
	ds_read_b128 v[200:203], v208 offset:51200
	ds_read_b128 v[204:207], v208 offset:52224
	s_mov_b32 m0, s0
	s_nop 0
	global_load_lds_dwordx4 v146, s[70:71]
	s_add_i32 m0, s0, 0x2000
	s_nop 0
	global_load_lds_dwordx4 v132, s[70:71]
	s_barrier
	s_waitcnt lgkmcnt(0)
	v_mfma_f32_16x16x32_bf16 v[116:119], v[192:195], v[160:163], v[116:119]
	v_mfma_f32_16x16x32_bf16 v[112:115], v[200:203], v[160:163], v[112:115]
	v_mfma_f32_16x16x32_bf16 v[100:103], v[192:195], v[168:171], v[100:103]
	v_mfma_f32_16x16x32_bf16 v[96:99], v[200:203], v[168:171], v[96:99]
	v_mfma_f32_16x16x32_bf16 v[84:87], v[192:195], v[176:179], v[84:87]
	v_mfma_f32_16x16x32_bf16 v[80:83], v[200:203], v[176:179], v[80:83]
	v_mfma_f32_16x16x32_bf16 v[68:71], v[192:195], v[184:187], v[68:71]
	v_mfma_f32_16x16x32_bf16 v[64:67], v[200:203], v[184:187], v[64:67]
	v_mfma_f32_16x16x32_bf16 v[116:119], v[196:199], v[164:167], v[116:119]
	v_mfma_f32_16x16x32_bf16 v[112:115], v[204:207], v[164:167], v[112:115]
	v_mfma_f32_16x16x32_bf16 v[100:103], v[196:199], v[172:175], v[100:103]
	v_mfma_f32_16x16x32_bf16 v[96:99], v[204:207], v[172:175], v[96:99]
	v_mfma_f32_16x16x32_bf16 v[84:87], v[196:199], v[180:183], v[84:87]
	v_mfma_f32_16x16x32_bf16 v[80:83], v[204:207], v[180:183], v[80:83]
	v_mfma_f32_16x16x32_bf16 v[68:71], v[196:199], v[188:191], v[68:71]
	v_mfma_f32_16x16x32_bf16 v[64:67], v[204:207], v[188:191], v[64:67]
	s_mov_b32 m0, s45
	s_barrier
; DI unsigned pk2(float lo, float hi) { unsigned r; asm("v_cvt_pk_bf16_f32 %0, %1, %2" : "=v"(r) : "v"(lo), "v"(hi)); return r; }
; #define G_STAGE(bufoff, gbase, voff) do { _Pragma("unroll") for (int _i = 0; _i < 2; ++_i) \
;         __builtin_amdgcn_global_load_lds((const unsigned*)((const char*)(gbase) + (voff)[_i]), (LAS unsigned*)(lds + (bufoff) + ldsw + _i * 8192), 16, 0, 0); } while (0)
; #define G_MMA(ai, bj, At, Bt) do { __builtin_amdgcn_s_setprio(1); _Pragma("unroll") for (int m = 0; m < 4; ++m) _Pragma("unroll") for (int n = 0; n < 2; ++n) _Pragma("unroll") for (int k = 0; k < 2; ++k) \
;         acc[ai][bj][m][n] = __builtin_amdgcn_mfma_f32_16x16x32_bf16(Bt[n][k], At[m][k], acc[ai][bj][m][n], 0, 0, 0); __builtin_amdgcn_s_setprio(0); } while (0)
; #define G_WAIT_V(n) asm volatile("s_waitcnt vmcnt(" #n ")" ::: "memory")
; #define G_BAR __builtin_amdgcn_s_barrier()
; template <class J>
; DI void gemm_phase(LAS unsigned char* lds, const J& job) {
;     ...
;       G_STAGE(G_SB(1, 1), b3 + hstepB, voffB);
;       G_WAIT_V(6); G_BAR; G_MMA(1, 1, At, B1); G_BAR;
;   DI void epi(const Acc& acc, const Unit& u, int wr, int wc, int fr, int fq) const {
; #pragma unroll
;     for (int ai = 0; ai < 2; ++ai)
; #pragma unroll
;       for (int m = 0; m < 4; ++m) {
;         const int rl = ai * HALF + wr * 64 + m * 16 + fr;
; #pragma unroll
;         for (int bj = 0; bj < 2; ++bj) {
;           const int col = u.pn * 256 + bj * HALF + wc * 32 + 8 * fq;
;           const f32x4 v0 = acc[ai][bj][m][0], v1 = acc[ai][bj][m][1];
;           const int row = u.pm * 256 + rl;
;           u32x4 o; o.x = pk2(v0.x, v0.y); o.y = pk2(v0.z, v0.w); o.z = pk2(v1.x, v1.y); o.w = pk2(v1.z, v1.w);
;           *(u32x4*)(proj + (size_t)row * NPROJ + col) = o;
;           if (u.pn >= 8 && u.pn < 12) {
;             const int isv = u.pn >= 10; const int cc = col - (isv ? C_BV : C_BK);
;             float* dst = out + (isv ? O_VP : O_KP) + ((size_t)l * TP + row) * 512 + cc;
;             *(f32x4*)dst = v0; *(f32x4*)(dst + 4) = v1;
	ds_read_b128 v[160:163], v151 offset:49152
	ds_read_b128 v[164:167], v151 offset:50176
	ds_read_b128 v[168:171], v151 offset:51200
	ds_read_b128 v[172:175], v151 offset:52224
	ds_read_b128 v[176:179], v151 offset:53248
	ds_read_b128 v[180:183], v151 offset:54272
	ds_read_b128 v[184:187], v151 offset:55296
	ds_read_b128 v[188:191], v151 offset:56320
	global_load_lds_dwordx4 v128, s[72:73]
	s_mov_b32 m0, s65
	s_nop 0
	global_load_lds_dwordx4 v130, s[72:73]
	s_barrier
	s_waitcnt lgkmcnt(0)
	v_mfma_f32_16x16x32_bf16 v[60:63], v[134:137], v[160:163], v[60:63]
	v_mfma_f32_16x16x32_bf16 v[56:59], v[152:155], v[160:163], v[56:59]
	v_mfma_f32_16x16x32_bf16 v[44:47], v[134:137], v[168:171], v[44:47]
	v_mfma_f32_16x16x32_bf16 v[40:43], v[152:155], v[168:171], v[40:43]
	v_mfma_f32_16x16x32_bf16 v[28:31], v[134:137], v[176:179], v[28:31]
	v_mfma_f32_16x16x32_bf16 v[24:27], v[152:155], v[176:179], v[24:27]
	v_mfma_f32_16x16x32_bf16 v[12:15], v[134:137], v[184:187], v[12:15]
	v_mfma_f32_16x16x32_bf16 v[8:11], v[152:155], v[184:187], v[8:11]
	v_mfma_f32_16x16x32_bf16 v[60:63], v[138:141], v[164:167], v[60:63]
	v_mfma_f32_16x16x32_bf16 v[56:59], v[156:159], v[164:167], v[56:59]
	v_mfma_f32_16x16x32_bf16 v[44:47], v[138:141], v[172:175], v[44:47]
	v_mfma_f32_16x16x32_bf16 v[40:43], v[156:159], v[172:175], v[40:43]
	v_mfma_f32_16x16x32_bf16 v[28:31], v[138:141], v[180:183], v[28:31]
	v_mfma_f32_16x16x32_bf16 v[24:27], v[156:159], v[180:183], v[24:27]
	v_mfma_f32_16x16x32_bf16 v[12:15], v[138:141], v[188:191], v[12:15]
	v_mfma_f32_16x16x32_bf16 v[8:11], v[156:159], v[188:191], v[8:11]
	s_barrier
	s_add_u32 s10, s70, 0x80000
	s_addc_u32 s11, s71, 0
	s_add_i32 s0, s1, s5
	s_mov_b32 m0, s0
	s_nop 0
	global_load_lds_dwordx4 v146, s[10:11]
	s_add_i32 m0, s0, 0x2000
	s_nop 0
	global_load_lds_dwordx4 v132, s[10:11]
	s_waitcnt vmcnt(6)
	s_barrier
	v_mfma_f32_16x16x32_bf16 v[52:55], v[192:195], v[160:163], v[52:55]
	v_mfma_f32_16x16x32_bf16 v[48:51], v[200:203], v[160:163], v[48:51]
	v_mfma_f32_16x16x32_bf16 v[36:39], v[192:195], v[168:171], v[36:39]
	v_mfma_f32_16x16x32_bf16 v[32:35], v[200:203], v[168:171], v[32:35]
	v_mfma_f32_16x16x32_bf16 v[20:23], v[192:195], v[176:179], v[20:23]
	v_mfma_f32_16x16x32_bf16 v[16:19], v[200:203], v[176:179], v[16:19]
	v_mfma_f32_16x16x32_bf16 v[4:7], v[192:195], v[184:187], v[4:7]
	v_mfma_f32_16x16x32_bf16 v[0:3], v[200:203], v[184:187], v[0:3]
	v_mfma_f32_16x16x32_bf16 v[52:55], v[196:199], v[164:167], v[52:55]
	v_mfma_f32_16x16x32_bf16 v[48:51], v[204:207], v[164:167], v[48:51]
	v_mfma_f32_16x16x32_bf16 v[36:39], v[196:199], v[172:175], v[36:39]
	v_mfma_f32_16x16x32_bf16 v[32:35], v[204:207], v[172:175], v[32:35]
	v_mfma_f32_16x16x32_bf16 v[20:23], v[196:199], v[180:183], v[20:23]
	v_mfma_f32_16x16x32_bf16 v[16:19], v[204:207], v[180:183], v[16:19]
	v_mfma_f32_16x16x32_bf16 v[4:7], v[196:199], v[188:191], v[4:7]
	v_mfma_f32_16x16x32_bf16 v[0:3], v[204:207], v[188:191], v[0:3]
	s_add_i32 s6, s6, 2
	s_addk_i32 s56, 0x100
	s_addk_i32 s7, 0x100
	s_cmp_gt_u32 s6, 29
	s_barrier
	s_cbranch_scc0 .LBB0_282
	v_mov_b32_e32 v135, v148
	v_mov_b32_e32 v134, v149
	s_lshl_b32 s0, s64, 8
	s_or_b32 s0, s0, s38
	v_lshl_add_u32 v134, v134, 3, s0
	s_lshl_b32 s0, s8, 8
	s_add_i32 s0, s0, s37
	v_add_u32_e32 v136, s0, v135
	s_and_b32 s0, s64, -4
	s_cmp_eq_u32 s0, 8
	s_cselect_b64 s[66:67], -1, 0
	s_cmp_gt_u32 s64, 9
	s_cselect_b64 s[6:7], -1, 0
	s_and_b64 s[6:7], s[6:7], exec
	s_movk_i32 s1, 0xf600
	v_mov_b64_e32 v[138:139], s[26:27]
	s_cselect_b32 s7, s1, 0xfffff800
	s_mov_b32 s1, 0x3040000
	v_ashrrev_i32_e32 v137, 31, v136
	v_mad_i64_i32 v[138:139], s[8:9], v136, s92, v[138:139]
	v_ashrrev_i32_e32 v135, 31, v134
	s_cselect_b32 s6, s1, 0x2040000
	s_cmp_lg_u32 s0, 8
	v_lshlrev_b64 v[140:141], 11, v[136:137]
	v_lshl_add_u64 v[142:143], v[134:135], 1, v[138:139]
	v_add_u32_e32 v138, s7, v134
	v_cvt_pk_bf16_f32 v152, v124, v125
	v_cvt_pk_bf16_f32 v153, v126, v127
	v_cvt_pk_bf16_f32 v154, v120, v121
	v_cvt_pk_bf16_f32 v155, v122, v123
	global_store_dwordx4 v[142:143], v[152:155], off
	s_cbranch_scc1 .LBB0_285
	s_lshl_b32 s0, s6, 2
	s_add_u32 s8, s83, s0
	s_addc_u32 s9, s86, 0
	v_lshl_add_u64 v[152:153], s[8:9], 0, v[140:141]
	v_ashrrev_i32_e32 v139, 31, v138
	v_lshl_add_u64 v[152:153], v[138:139], 2, v[152:153]
	global_store_dwordx4 v[152:153], v[124:127], off
	global_store_dwordx4 v[152:153], v[120:123], off offset:16
